# non-temporal hint on the scan loaders' record loads and the o-norm loads (read-once streams); on v61
# baseline (speedup 1.0000x reference)
; #define LAS __attribute__((address_space(3)))
; __device__ __forceinline__ void scan_bh(LAS unsigned char* lds, const ScanP& P, int b, int h, int half, int tid, int lane, int wave) {
;     const bool cw = wave < 4;
;     const int r = lane & 15, q8 = lane >> 4, ct = half * 4 + (wave & 3), c0 = ct * 16;
;     if (!cw) {
;         const int lt = tid - 256, wrow = lt >> 4, wc16 = lt & 15, arow = lt >> 3, ac16 = lt & 7;
;         const int wperm = (wc16 >> 2) * 32 + ((((wc16 & 3) * 8) & 15) >> 2) * 8 + (((wc16 & 3) * 8) >> 4) * 4, aperm = (ac16 >> 2) * 32 + ((((ac16 & 3) * 8) & 15) >> 2) * 8 + (((ac16 & 3) * 8) >> 4) * 4;
;         const unsigned oW = (unsigned)TR_W + (unsigned)(wrow * 128 + wc16 * 8) * 2u, oQ = oW + (unsigned)(TR_Q - TR_W), oA = (unsigned)TR_A + (unsigned)(arow * 64 + ac16 * 8) * 2u, oK = oA + (unsigned)(TR_K - TR_A);
;         const unsigned lW = (unsigned)(wrow * PS + wperm) * 2u, lA = (unsigned)(arow * TS + aperm) * 2u;
;         u32x4 sa[14], sb[14];
;     ...
;         L_LOAD(0, sa); L_STORE(lds, sa); L_LOAD(1, sa);
;         __syncthreads();
.LBB0_514:
	s_and_b64 vcc, exec, s[4:5]
	s_mov_b32 s54, s13
	s_mov_b64 s[20:21], 0x28e00000
	s_cbranch_vccz .LBB0_534
	s_mov_b32 s4, -1
	s_mov_b32 s10, s2
	s_waitcnt vmcnt(0)
	v_mbcnt_lo_u32_b32 v0, s4, 0
	v_mbcnt_hi_u32_b32 v0, s4, v0
	v_or_b32_e32 v145, s3, v0
	s_mov_b64 s[4:5], s[0:1]
	s_and_b32 s8, s10, 7
	v_mov_b64_e32 v[0:1], s[4:5]
	s_waitcnt lgkmcnt(0)
	flat_load_dwordx4 v[0:3], v[0:1] offset:144
	v_readfirstlane_b32 s4, v145
	s_ashr_i32 s9, s10, 4
	s_ashr_i32 s11, s4, 6
	s_mov_b64 s[4:5], 0x22400000
	v_and_b32_e32 v144, 15, v145
	s_cmp_gt_i32 s11, 3
	s_waitcnt vmcnt(0) lgkmcnt(0)
	v_lshl_add_u64 v[116:117], v[2:3], 0, s[4:5]
	s_mov_b64 s[4:5], -1
	s_cbranch_scc0 .LBB0_525
	v_add_u32_e32 v4, 0xffffff00, v145
	v_ashrrev_i32_e32 v147, 4, v4
	v_ashrrev_i32_e32 v150, 3, v4
	v_lshlrev_b32_e32 v146, 3, v144
	v_lshlrev_b32_e32 v148, 1, v145
	v_and_b32_e32 v151, 0x60, v146
	v_lshlrev_b32_e32 v146, 4, v145
	v_and_b32_e32 v148, 4, v148
	v_lshlrev_b32_e32 v149, 3, v145
	v_and_or_b32 v146, v146, 16, v148
	v_and_b32_e32 v156, 32, v149
	v_mad_u64_u32 v[148:149], s[4:5], v147, s50, v[146:147]
	s_movk_i32 s4, 0x48
	s_nop 0
	v_mad_u64_u32 v[146:147], s[4:5], v150, s4, v[146:147]
	v_add_lshl_u32 v160, v148, v151, 1
	v_add_u32_e32 v147, 0, v160
	v_add_lshl_u32 v146, v146, v156, 1
	v_mov_b32_e32 v247, v160
	v_add_u32_e32 v248, 0xf400, v160
	v_mov_b32_e32 v249, v146
	v_add_u32_e32 v250, 0xf400, v146
	v_lshlrev_b32_e32 v5, 4, v4
	v_add_u32_e32 v240, 0x1000, v5
	v_add_u32_e32 v241, 0x3000, v5
	v_add_u32_e32 v242, 0x5000, v5
	v_add_u32_e32 v243, 0x7000, v5
	v_add_u32_e32 v244, 0x9000, v5
	v_add_u32_e32 v245, 0xb000, v5
	v_add_u32_e32 v246, 0xd000, v5
	v_readfirstlane_b32 s6, v116
	v_readfirstlane_b32 s7, v117
	s_lshl_b32 s18, s9, 8
	s_or_b32 s18, s18, s8
	s_mul_hi_u32 s15, s18, 0x1a000
	s_mul_i32 s14, s18, 0x1a000
	s_add_u32 s14, s14, s6
	s_addc_u32 s15, s15, s7
	s_mov_b32 s16, 0
	global_load_dwordx4 v[0:3], v240, s[14:15] offset:-4096 nt
	global_load_dwordx4 v[4:7], v240, s[14:15] nt
	global_load_dwordx4 v[8:11], v241, s[14:15] offset:-4096 nt
	global_load_dwordx4 v[12:15], v241, s[14:15] nt
	global_load_dwordx4 v[16:19], v242, s[14:15] offset:-4096 nt
	global_load_dwordx4 v[20:23], v242, s[14:15] nt
	global_load_dwordx4 v[24:27], v243, s[14:15] offset:-4096 nt
	global_load_dwordx4 v[28:31], v243, s[14:15] nt
	global_load_dwordx4 v[32:35], v244, s[14:15] offset:-4096 nt
	global_load_dwordx4 v[36:39], v244, s[14:15] nt
	global_load_dwordx4 v[40:43], v245, s[14:15] offset:-4096 nt
	global_load_dwordx4 v[44:47], v245, s[14:15] nt
	global_load_dwordx4 v[48:51], v246, s[14:15] offset:-4096 nt
	global_load_dwordx4 v[52:55], v246, s[14:15] nt
	s_add_u32 s14, s14, 0xd0000
	s_addc_u32 s15, s15, 0
	global_load_dwordx4 v[56:59], v240, s[14:15] offset:-4096 nt
	global_load_dwordx4 v[60:63], v240, s[14:15] nt
	global_load_dwordx4 v[64:67], v241, s[14:15] offset:-4096 nt
	global_load_dwordx4 v[68:71], v241, s[14:15] nt
	global_load_dwordx4 v[72:75], v242, s[14:15] offset:-4096 nt
	global_load_dwordx4 v[76:79], v242, s[14:15] nt
	global_load_dwordx4 v[80:83], v243, s[14:15] offset:-4096 nt
	global_load_dwordx4 v[84:87], v243, s[14:15] nt
	global_load_dwordx4 v[88:91], v244, s[14:15] offset:-4096 nt
	global_load_dwordx4 v[92:95], v244, s[14:15] nt
	global_load_dwordx4 v[96:99], v245, s[14:15] offset:-4096 nt
	global_load_dwordx4 v[100:103], v245, s[14:15] nt
	global_load_dwordx4 v[104:107], v246, s[14:15] offset:-4096 nt
	global_load_dwordx4 v[108:111], v246, s[14:15] nt
	s_add_u32 s14, s14, 0xd0000
	s_addc_u32 s15, s15, 0
	global_load_dwordx4 v[112:115], v240, s[14:15] offset:-4096 nt
	global_load_dwordx4 v[116:119], v240, s[14:15] nt
	global_load_dwordx4 v[120:123], v241, s[14:15] offset:-4096 nt
	global_load_dwordx4 v[124:127], v241, s[14:15] nt
	global_load_dwordx4 v[128:131], v242, s[14:15] offset:-4096 nt
	global_load_dwordx4 v[132:135], v242, s[14:15] nt
	global_load_dwordx4 v[136:139], v243, s[14:15] offset:-4096 nt
	global_load_dwordx4 v[140:143], v243, s[14:15] nt
	global_load_dwordx4 v[144:147], v244, s[14:15] offset:-4096 nt
	global_load_dwordx4 v[148:151], v244, s[14:15] nt
	global_load_dwordx4 v[156:159], v245, s[14:15] offset:-4096 nt
	global_load_dwordx4 v[160:163], v245, s[14:15] nt
	global_load_dwordx4 v[164:167], v246, s[14:15] offset:-4096 nt
	global_load_dwordx4 v[168:171], v246, s[14:15] nt
	s_add_u32 s14, s14, 0xd0000
	s_addc_u32 s15, s15, 0
	global_load_dwordx4 v[172:175], v240, s[14:15] offset:-4096 nt
	global_load_dwordx4 v[176:179], v240, s[14:15] nt
	global_load_dwordx4 v[180:183], v241, s[14:15] offset:-4096 nt
	global_load_dwordx4 v[184:187], v241, s[14:15] nt
	global_load_dwordx4 v[188:191], v242, s[14:15] offset:-4096 nt
	global_load_dwordx4 v[200:203], v242, s[14:15] nt
	global_load_dwordx4 v[204:207], v243, s[14:15] offset:-4096 nt
	global_load_dwordx4 v[208:211], v243, s[14:15] nt
	global_load_dwordx4 v[212:215], v244, s[14:15] offset:-4096 nt
	global_load_dwordx4 v[216:219], v244, s[14:15] nt
	global_load_dwordx4 v[220:223], v245, s[14:15] offset:-4096 nt
	global_load_dwordx4 v[224:227], v245, s[14:15] nt
	global_load_dwordx4 v[228:231], v246, s[14:15] offset:-4096 nt
	global_load_dwordx4 v[232:235], v246, s[14:15] nt
	s_add_u32 s14, s14, 0xd0000
	s_addc_u32 s15, s15, 0
	s_waitcnt vmcnt(55)
	ds_write_b64 v247, v[0:1]
	ds_write_b64 v247, v[2:3] offset:16
	s_waitcnt vmcnt(54)
	ds_write_b64 v247, v[4:5] offset:4352
	ds_write_b64 v247, v[6:7] offset:4368
	s_waitcnt vmcnt(53)
	ds_write_b64 v247, v[8:9] offset:8704
	ds_write_b64 v247, v[10:11] offset:8720
	s_waitcnt vmcnt(52)
	ds_write_b64 v247, v[12:13] offset:13056
	ds_write_b64 v247, v[14:15] offset:13072
	s_waitcnt vmcnt(51)
	ds_write_b64 v247, v[16:17] offset:17408
	ds_write_b64 v247, v[18:19] offset:17424
	s_waitcnt vmcnt(50)
	ds_write_b64 v247, v[20:21] offset:21760
	ds_write_b64 v247, v[22:23] offset:21776
	s_waitcnt vmcnt(49)
	ds_write_b64 v247, v[24:25] offset:26112
	ds_write_b64 v247, v[26:27] offset:26128
	s_waitcnt vmcnt(48)
	ds_write_b64 v247, v[28:29] offset:30464
	ds_write_b64 v247, v[30:31] offset:30480
	s_waitcnt vmcnt(47)
	ds_write_b64 v249, v[32:33] offset:34816
	ds_write_b64 v249, v[34:35] offset:34832
	s_waitcnt vmcnt(46)
	ds_write_b64 v249, v[36:37] offset:39424
	ds_write_b64 v249, v[38:39] offset:39440
	s_waitcnt vmcnt(45)
	ds_write_b64 v249, v[40:41] offset:44032
	ds_write_b64 v249, v[42:43] offset:44048
	s_waitcnt vmcnt(44)
	ds_write_b64 v249, v[44:45] offset:48640
	ds_write_b64 v249, v[46:47] offset:48656
	s_waitcnt vmcnt(43)
	ds_write_b64 v249, v[48:49] offset:53248
	ds_write_b64 v249, v[50:51] offset:53264
	s_waitcnt vmcnt(42)
	ds_write_b64 v249, v[52:53] offset:57856
	ds_write_b64 v249, v[54:55] offset:57872
	s_waitcnt lgkmcnt(0)
	s_barrier
; #define LBAR() do { asm volatile("s_waitcnt lgkmcnt(0)" ::: "memory"); __builtin_amdgcn_s_barrier(); asm volatile("" ::: "memory"); } while (0)
; __device__ __forceinline__ void scan_bh(LAS unsigned char* lds, const ScanP& P, int b, int h, int half, int tid, int lane, int wave) {
;     ...
;         L_LOAD(0, sa); L_STORE(lds, sa); L_LOAD(1, sa);
;         __syncthreads();
; #pragma unroll 1
;         for (int n = 0; n < 32; n += 2) {
;             if (n + 2 < 32) L_LOAD(n + 2, sb);
;             L_STORE(lds + ((n + 1) & 1) * SB_SZ, sa);
;             LBAR();
;             if (n + 3 < 32) L_LOAD(n + 3, sa);
;             if (n + 2 < 32) L_STORE(lds + ((n + 2) & 1) * SB_SZ, sb);
;             LBAR();
;         }
.Lscan_ld:
	global_load_dwordx4 v[0:3], v240, s[14:15] offset:-4096 nt
	global_load_dwordx4 v[4:7], v240, s[14:15] nt
	global_load_dwordx4 v[8:11], v241, s[14:15] offset:-4096 nt
	global_load_dwordx4 v[12:15], v241, s[14:15] nt
	global_load_dwordx4 v[16:19], v242, s[14:15] offset:-4096 nt
	global_load_dwordx4 v[20:23], v242, s[14:15] nt
	global_load_dwordx4 v[24:27], v243, s[14:15] offset:-4096 nt
	global_load_dwordx4 v[28:31], v243, s[14:15] nt
	global_load_dwordx4 v[32:35], v244, s[14:15] offset:-4096 nt
	global_load_dwordx4 v[36:39], v244, s[14:15] nt
	global_load_dwordx4 v[40:43], v245, s[14:15] offset:-4096 nt
	global_load_dwordx4 v[44:47], v245, s[14:15] nt
	global_load_dwordx4 v[48:51], v246, s[14:15] offset:-4096 nt
	global_load_dwordx4 v[52:55], v246, s[14:15] nt
	s_cmp_lt_u32 s16, 27
	s_cselect_b32 s19, 0xd0000, 0
	s_add_u32 s14, s14, s19
	s_addc_u32 s15, s15, 0
	s_waitcnt vmcnt(55)
	ds_write_b64 v248, v[56:57]
	ds_write_b64 v248, v[58:59] offset:16
	s_waitcnt vmcnt(54)
	ds_write_b64 v248, v[60:61] offset:4352
	ds_write_b64 v248, v[62:63] offset:4368
	s_waitcnt vmcnt(53)
	ds_write_b64 v248, v[64:65] offset:8704
	ds_write_b64 v248, v[66:67] offset:8720
	s_waitcnt vmcnt(52)
	ds_write_b64 v248, v[68:69] offset:13056
	ds_write_b64 v248, v[70:71] offset:13072
	s_waitcnt vmcnt(51)
	ds_write_b64 v248, v[72:73] offset:17408
	ds_write_b64 v248, v[74:75] offset:17424
	s_waitcnt vmcnt(50)
	ds_write_b64 v248, v[76:77] offset:21760
	ds_write_b64 v248, v[78:79] offset:21776
	s_waitcnt vmcnt(49)
	ds_write_b64 v248, v[80:81] offset:26112
	ds_write_b64 v248, v[82:83] offset:26128
	s_waitcnt vmcnt(48)
	ds_write_b64 v248, v[84:85] offset:30464
	ds_write_b64 v248, v[86:87] offset:30480
	s_waitcnt vmcnt(47)
	ds_write_b64 v250, v[88:89] offset:34816
	ds_write_b64 v250, v[90:91] offset:34832
	s_waitcnt vmcnt(46)
	ds_write_b64 v250, v[92:93] offset:39424
	ds_write_b64 v250, v[94:95] offset:39440
	s_waitcnt vmcnt(45)
	ds_write_b64 v250, v[96:97] offset:44032
	ds_write_b64 v250, v[98:99] offset:44048
	s_waitcnt vmcnt(44)
	ds_write_b64 v250, v[100:101] offset:48640
	ds_write_b64 v250, v[102:103] offset:48656
	s_waitcnt vmcnt(43)
	ds_write_b64 v250, v[104:105] offset:53248
	ds_write_b64 v250, v[106:107] offset:53264
	s_waitcnt vmcnt(42)
	ds_write_b64 v250, v[108:109] offset:57856
	ds_write_b64 v250, v[110:111] offset:57872
	s_waitcnt lgkmcnt(0)
	s_barrier
	s_add_i32 s16, s16, 1
	s_cmp_eq_u32 s16, 31
	s_cbranch_scc1 .Lscan_ld_last
	global_load_dwordx4 v[56:59], v240, s[14:15] offset:-4096 nt
	global_load_dwordx4 v[60:63], v240, s[14:15] nt
	global_load_dwordx4 v[64:67], v241, s[14:15] offset:-4096 nt
	global_load_dwordx4 v[68:71], v241, s[14:15] nt
	global_load_dwordx4 v[72:75], v242, s[14:15] offset:-4096 nt
	global_load_dwordx4 v[76:79], v242, s[14:15] nt
	global_load_dwordx4 v[80:83], v243, s[14:15] offset:-4096 nt
	global_load_dwordx4 v[84:87], v243, s[14:15] nt
	global_load_dwordx4 v[88:91], v244, s[14:15] offset:-4096 nt
	global_load_dwordx4 v[92:95], v244, s[14:15] nt
	global_load_dwordx4 v[96:99], v245, s[14:15] offset:-4096 nt
	global_load_dwordx4 v[100:103], v245, s[14:15] nt
	global_load_dwordx4 v[104:107], v246, s[14:15] offset:-4096 nt
	global_load_dwordx4 v[108:111], v246, s[14:15] nt
	s_cmp_lt_u32 s16, 27
	s_cselect_b32 s19, 0xd0000, 0
	s_add_u32 s14, s14, s19
	s_addc_u32 s15, s15, 0
	s_waitcnt vmcnt(55)
	ds_write_b64 v247, v[112:113]
	ds_write_b64 v247, v[114:115] offset:16
	s_waitcnt vmcnt(54)
	ds_write_b64 v247, v[116:117] offset:4352
	ds_write_b64 v247, v[118:119] offset:4368
	s_waitcnt vmcnt(53)
	ds_write_b64 v247, v[120:121] offset:8704
	ds_write_b64 v247, v[122:123] offset:8720
	s_waitcnt vmcnt(52)
	ds_write_b64 v247, v[124:125] offset:13056
	ds_write_b64 v247, v[126:127] offset:13072
	s_waitcnt vmcnt(51)
	ds_write_b64 v247, v[128:129] offset:17408
	ds_write_b64 v247, v[130:131] offset:17424
	s_waitcnt vmcnt(50)
	ds_write_b64 v247, v[132:133] offset:21760
	ds_write_b64 v247, v[134:135] offset:21776
	s_waitcnt vmcnt(49)
	ds_write_b64 v247, v[136:137] offset:26112
	ds_write_b64 v247, v[138:139] offset:26128
	s_waitcnt vmcnt(48)
	ds_write_b64 v247, v[140:141] offset:30464
	ds_write_b64 v247, v[142:143] offset:30480
	s_waitcnt vmcnt(47)
	ds_write_b64 v249, v[144:145] offset:34816
	ds_write_b64 v249, v[146:147] offset:34832
	s_waitcnt vmcnt(46)
	ds_write_b64 v249, v[148:149] offset:39424
	ds_write_b64 v249, v[150:151] offset:39440
	s_waitcnt vmcnt(45)
	ds_write_b64 v249, v[156:157] offset:44032
	ds_write_b64 v249, v[158:159] offset:44048
	s_waitcnt vmcnt(44)
	ds_write_b64 v249, v[160:161] offset:48640
	ds_write_b64 v249, v[162:163] offset:48656
	s_waitcnt vmcnt(43)
	ds_write_b64 v249, v[164:165] offset:53248
	ds_write_b64 v249, v[166:167] offset:53264
	s_waitcnt vmcnt(42)
	ds_write_b64 v249, v[168:169] offset:57856
	ds_write_b64 v249, v[170:171] offset:57872
	s_waitcnt lgkmcnt(0)
	s_barrier
	s_add_i32 s16, s16, 1
	s_cmp_eq_u32 s16, 31
	s_cbranch_scc1 .Lscan_ld_last
; #define LBAR() do { asm volatile("s_waitcnt lgkmcnt(0)" ::: "memory"); __builtin_amdgcn_s_barrier(); asm volatile("" ::: "memory"); } while (0)
; __device__ __forceinline__ void scan_bh(LAS unsigned char* lds, const ScanP& P, int b, int h, int half, int tid, int lane, int wave) {
;     ...
;         L_LOAD(0, sa); L_STORE(lds, sa); L_LOAD(1, sa);
;         __syncthreads();
; #pragma unroll 1
;         for (int n = 0; n < 32; n += 2) {
;             if (n + 2 < 32) L_LOAD(n + 2, sb);
;             L_STORE(lds + ((n + 1) & 1) * SB_SZ, sa);
;             LBAR();
;             if (n + 3 < 32) L_LOAD(n + 3, sa);
;             if (n + 2 < 32) L_STORE(lds + ((n + 2) & 1) * SB_SZ, sb);
;             LBAR();
;         }
	global_load_dwordx4 v[112:115], v240, s[14:15] offset:-4096 nt
	global_load_dwordx4 v[116:119], v240, s[14:15] nt
	global_load_dwordx4 v[120:123], v241, s[14:15] offset:-4096 nt
	global_load_dwordx4 v[124:127], v241, s[14:15] nt
	global_load_dwordx4 v[128:131], v242, s[14:15] offset:-4096 nt
	global_load_dwordx4 v[132:135], v242, s[14:15] nt
	global_load_dwordx4 v[136:139], v243, s[14:15] offset:-4096 nt
	global_load_dwordx4 v[140:143], v243, s[14:15] nt
	global_load_dwordx4 v[144:147], v244, s[14:15] offset:-4096 nt
	global_load_dwordx4 v[148:151], v244, s[14:15] nt
	global_load_dwordx4 v[156:159], v245, s[14:15] offset:-4096 nt
	global_load_dwordx4 v[160:163], v245, s[14:15] nt
	global_load_dwordx4 v[164:167], v246, s[14:15] offset:-4096 nt
	global_load_dwordx4 v[168:171], v246, s[14:15] nt
	s_cmp_lt_u32 s16, 27
	s_cselect_b32 s19, 0xd0000, 0
	s_add_u32 s14, s14, s19
	s_addc_u32 s15, s15, 0
	s_waitcnt vmcnt(55)
	ds_write_b64 v248, v[172:173]
	ds_write_b64 v248, v[174:175] offset:16
	s_waitcnt vmcnt(54)
	ds_write_b64 v248, v[176:177] offset:4352
	ds_write_b64 v248, v[178:179] offset:4368
	s_waitcnt vmcnt(53)
	ds_write_b64 v248, v[180:181] offset:8704
	ds_write_b64 v248, v[182:183] offset:8720
	s_waitcnt vmcnt(52)
	ds_write_b64 v248, v[184:185] offset:13056
	ds_write_b64 v248, v[186:187] offset:13072
	s_waitcnt vmcnt(51)
	ds_write_b64 v248, v[188:189] offset:17408
	ds_write_b64 v248, v[190:191] offset:17424
	s_waitcnt vmcnt(50)
	ds_write_b64 v248, v[200:201] offset:21760
	ds_write_b64 v248, v[202:203] offset:21776
	s_waitcnt vmcnt(49)
	ds_write_b64 v248, v[204:205] offset:26112
	ds_write_b64 v248, v[206:207] offset:26128
	s_waitcnt vmcnt(48)
	ds_write_b64 v248, v[208:209] offset:30464
	ds_write_b64 v248, v[210:211] offset:30480
	s_waitcnt vmcnt(47)
	ds_write_b64 v250, v[212:213] offset:34816
	ds_write_b64 v250, v[214:215] offset:34832
	s_waitcnt vmcnt(46)
	ds_write_b64 v250, v[216:217] offset:39424
	ds_write_b64 v250, v[218:219] offset:39440
	s_waitcnt vmcnt(45)
	ds_write_b64 v250, v[220:221] offset:44032
	ds_write_b64 v250, v[222:223] offset:44048
	s_waitcnt vmcnt(44)
	ds_write_b64 v250, v[224:225] offset:48640
	ds_write_b64 v250, v[226:227] offset:48656
	s_waitcnt vmcnt(43)
	ds_write_b64 v250, v[228:229] offset:53248
	ds_write_b64 v250, v[230:231] offset:53264
	s_waitcnt vmcnt(42)
	ds_write_b64 v250, v[232:233] offset:57856
	ds_write_b64 v250, v[234:235] offset:57872
	s_waitcnt lgkmcnt(0)
	s_barrier
	s_add_i32 s16, s16, 1
	s_cmp_eq_u32 s16, 31
	s_cbranch_scc1 .Lscan_ld_last
	global_load_dwordx4 v[172:175], v240, s[14:15] offset:-4096 nt
	global_load_dwordx4 v[176:179], v240, s[14:15] nt
	global_load_dwordx4 v[180:183], v241, s[14:15] offset:-4096 nt
	global_load_dwordx4 v[184:187], v241, s[14:15] nt
	global_load_dwordx4 v[188:191], v242, s[14:15] offset:-4096 nt
	global_load_dwordx4 v[200:203], v242, s[14:15] nt
	global_load_dwordx4 v[204:207], v243, s[14:15] offset:-4096 nt
	global_load_dwordx4 v[208:211], v243, s[14:15] nt
	global_load_dwordx4 v[212:215], v244, s[14:15] offset:-4096 nt
	global_load_dwordx4 v[216:219], v244, s[14:15] nt
	global_load_dwordx4 v[220:223], v245, s[14:15] offset:-4096 nt
	global_load_dwordx4 v[224:227], v245, s[14:15] nt
	global_load_dwordx4 v[228:231], v246, s[14:15] offset:-4096 nt
	global_load_dwordx4 v[232:235], v246, s[14:15] nt
	s_cmp_lt_u32 s16, 27
	s_cselect_b32 s19, 0xd0000, 0
	s_add_u32 s14, s14, s19
	s_addc_u32 s15, s15, 0
	s_waitcnt vmcnt(55)
	ds_write_b64 v247, v[0:1]
	ds_write_b64 v247, v[2:3] offset:16
	s_waitcnt vmcnt(54)
	ds_write_b64 v247, v[4:5] offset:4352
	ds_write_b64 v247, v[6:7] offset:4368
	s_waitcnt vmcnt(53)
	ds_write_b64 v247, v[8:9] offset:8704
	ds_write_b64 v247, v[10:11] offset:8720
	s_waitcnt vmcnt(52)
	ds_write_b64 v247, v[12:13] offset:13056
	ds_write_b64 v247, v[14:15] offset:13072
	s_waitcnt vmcnt(51)
	ds_write_b64 v247, v[16:17] offset:17408
	ds_write_b64 v247, v[18:19] offset:17424
	s_waitcnt vmcnt(50)
	ds_write_b64 v247, v[20:21] offset:21760
	ds_write_b64 v247, v[22:23] offset:21776
	s_waitcnt vmcnt(49)
	ds_write_b64 v247, v[24:25] offset:26112
	ds_write_b64 v247, v[26:27] offset:26128
	s_waitcnt vmcnt(48)
	ds_write_b64 v247, v[28:29] offset:30464
	ds_write_b64 v247, v[30:31] offset:30480
	s_waitcnt vmcnt(47)
	ds_write_b64 v249, v[32:33] offset:34816
	ds_write_b64 v249, v[34:35] offset:34832
	s_waitcnt vmcnt(46)
	ds_write_b64 v249, v[36:37] offset:39424
	ds_write_b64 v249, v[38:39] offset:39440
	s_waitcnt vmcnt(45)
	ds_write_b64 v249, v[40:41] offset:44032
	ds_write_b64 v249, v[42:43] offset:44048
	s_waitcnt vmcnt(44)
	ds_write_b64 v249, v[44:45] offset:48640
	ds_write_b64 v249, v[46:47] offset:48656
	s_waitcnt vmcnt(43)
	ds_write_b64 v249, v[48:49] offset:53248
	ds_write_b64 v249, v[50:51] offset:53264
	s_waitcnt vmcnt(42)
	ds_write_b64 v249, v[52:53] offset:57856
	ds_write_b64 v249, v[54:55] offset:57872
	s_waitcnt lgkmcnt(0)
	s_barrier
	s_add_i32 s16, s16, 1
	s_cmp_eq_u32 s16, 31
	s_cbranch_scc1 .Lscan_ld_last
	s_branch .Lscan_ld

; __device__ __forceinline__ float bflo(unsigned w) { return __uint_as_float(w << 16); }
; __device__ __forceinline__ void onorm_pass(const float* obuf, const bf16_t* z, const float* ong, bf16_t* ycat, int gw, int NGW, int lane) {
;     const int cl = (lane & 7) * 16;
;     f32x4 g[4];
; #pragma unroll
;     for (int i = 0; i < 4; ++i) g[i] = *(const f32x4*)(ong + cl + 4 * i);
; #pragma unroll 2
;     for (int row = gw; row < MP; row += NGW) {
;         const float* op = obuf + (size_t)row * 1024 + lane * 16; const bf16_t* zp = z + (size_t)row * NZ + 7168 + lane * 16;
;         f32x4 v[4]; float ss = 0.f;
; #pragma unroll
;         for (int i = 0; i < 4; ++i) { v[i] = *(const f32x4*)(op + 4 * i); ss += (v[i].x * v[i].x + v[i].y * v[i].y) + (v[i].z * v[i].z + v[i].w * v[i].w); }
;         const u32x4 g0 = *(const u32x4*)zp, g1 = *(const u32x4*)(zp + 8);
;         ss += __builtin_bit_cast(float, __builtin_amdgcn_update_dpp(0, __builtin_bit_cast(int, ss), 0xB1, 0xF, 0xF, true));
;         ss += __builtin_bit_cast(float, __builtin_amdgcn_update_dpp(0, __builtin_bit_cast(int, ss), 0x4E, 0xF, 0xF, true));
;         ss += __builtin_bit_cast(float, __builtin_amdgcn_update_dpp(0, __builtin_bit_cast(int, ss), 0x141, 0xF, 0xF, true));
;         const float rstd = rsq_f(ss * (1.f / HD) + EPS);
;         float y[16];
;         y[0] = v[0].x * rstd * g[0].x * silu_f(bflo(g0.x)); y[1] = v[0].y * rstd * g[0].y * silu_f(bfhi(g0.x)); y[2] = v[0].z * rstd * g[0].z * silu_f(bflo(g0.y)); y[3] = v[0].w * rstd * g[0].w * silu_f(bfhi(g0.y));
;         y[4] = v[1].x * rstd * g[1].x * silu_f(bflo(g0.z)); y[5] = v[1].y * rstd * g[1].y * silu_f(bfhi(g0.z)); y[6] = v[1].z * rstd * g[1].z * silu_f(bflo(g0.w)); y[7] = v[1].w * rstd * g[1].w * silu_f(bfhi(g0.w));
;         y[8] = v[2].x * rstd * g[2].x * silu_f(bflo(g1.x)); y[9] = v[2].y * rstd * g[2].y * silu_f(bfhi(g1.x)); y[10] = v[2].z * rstd * g[2].z * silu_f(bflo(g1.y)); y[11] = v[2].w * rstd * g[2].w * silu_f(bfhi(g1.y));
;         y[12] = v[3].x * rstd * g[3].x * silu_f(bflo(g1.z)); y[13] = v[3].y * rstd * g[3].y * silu_f(bfhi(g1.z)); y[14] = v[3].z * rstd * g[3].z * silu_f(bflo(g1.w)); y[15] = v[3].w * rstd * g[3].w * silu_f(bfhi(g1.w));
;         bf16_t* yp = ycat + (size_t)row * DM + 1024 + lane * 16;
;         *(u32x4*)yp = pack8(y); *(u32x4*)(yp + 8) = pack8(y + 8);
.LBB0_589:
	s_mov_b64 s[6:7], 0x13c03800
	v_lshl_add_u64 v[200:201], v[28:29], 0, v[50:51]
	v_lshl_add_u64 v[200:201], v[200:201], 0, s[8:9]
	v_lshl_add_u64 v[202:203], v[28:29], 0, v[48:49]
	v_lshl_add_u64 v[202:203], v[202:203], 0, s[6:7]
	global_load_dwordx4 v[68:71], v[200:201], off nt
	global_load_dwordx4 v[72:75], v[200:201], off offset:16 nt
	global_load_dwordx4 v[76:79], v[200:201], off offset:32 nt
	global_load_dwordx4 v[80:83], v[200:201], off offset:48 nt
	global_load_dwordx4 v[84:87], v[202:203], off nt
	global_load_dwordx4 v[88:91], v[202:203], off offset:16 nt
	v_lshl_add_u64 v[200:201], v[200:201], 0, s[84:85]
	v_lshl_add_u64 v[202:203], v[202:203], 0, s[60:61]
	global_load_dwordx4 v[92:95], v[200:201], off nt
	global_load_dwordx4 v[96:99], v[200:201], off offset:16 nt
	global_load_dwordx4 v[100:103], v[200:201], off offset:32 nt
	global_load_dwordx4 v[104:107], v[200:201], off offset:48 nt
	global_load_dwordx4 v[108:111], v[202:203], off nt
	global_load_dwordx4 v[112:115], v[202:203], off offset:16 nt
	v_lshl_add_u64 v[200:201], v[200:201], 0, s[84:85]
	v_lshl_add_u64 v[202:203], v[202:203], 0, s[60:61]
	global_load_dwordx4 v[116:119], v[200:201], off nt
	global_load_dwordx4 v[120:123], v[200:201], off offset:16 nt
	global_load_dwordx4 v[124:127], v[200:201], off offset:32 nt
	global_load_dwordx4 v[128:131], v[200:201], off offset:48 nt
	global_load_dwordx4 v[132:135], v[202:203], off nt
	global_load_dwordx4 v[136:139], v[202:203], off offset:16 nt
	v_lshl_add_u64 v[200:201], v[200:201], 0, s[84:85]
	v_lshl_add_u64 v[202:203], v[202:203], 0, s[60:61]
	global_load_dwordx4 v[140:143], v[200:201], off nt
	global_load_dwordx4 v[144:147], v[200:201], off offset:16 nt
	global_load_dwordx4 v[148:151], v[200:201], off offset:32 nt
	global_load_dwordx4 v[156:159], v[200:201], off offset:48 nt
	global_load_dwordx4 v[160:163], v[202:203], off nt
	global_load_dwordx4 v[164:167], v[202:203], off offset:16 nt
	v_lshl_add_u64 v[200:201], v[200:201], 0, s[84:85]
	v_lshl_add_u64 v[202:203], v[202:203], 0, s[60:61]
	v_lshl_add_u64 v[16:17], v[28:29], 0, v[50:51]
	v_lshl_add_u64 v[18:19], v[16:17], 0, s[8:9]
	v_add_co_u32_e32 v16, vcc, 0x28e00000, v16
	s_mov_b64 s[6:7], 0x13c03800
	s_nop 0
	v_addc_co_u32_e32 v17, vcc, 0, v17, vcc
	s_waitcnt vmcnt(18)
	v_mov_b32_e32 v52, v68
	v_mov_b32_e32 v53, v69
	v_mov_b32_e32 v54, v70
	v_mov_b32_e32 v55, v71
	v_mov_b32_e32 v20, v76
	v_mov_b32_e32 v21, v77
	v_mov_b32_e32 v22, v78
	v_mov_b32_e32 v23, v79
	v_mov_b32_e32 v24, v72
	v_mov_b32_e32 v25, v73
	v_mov_b32_e32 v26, v74
	v_mov_b32_e32 v27, v75
	s_nop 0
	v_mov_b32_e32 v16, v80
	v_mov_b32_e32 v17, v81
	v_mov_b32_e32 v18, v82
	v_mov_b32_e32 v19, v83
	s_mov_b32 s5, 0x20300000
	s_addk_i32 s4, 0x400
	v_lshl_add_u64 v[50:51], v[50:51], 0, s[84:85]
	s_cmpk_gt_i32 s4, 0x1bff
	s_nop 0
	v_pk_mul_f32 v[56:57], v[54:55], v[54:55]
	v_pk_mul_f32 v[58:59], v[52:53], v[52:53]
	s_nop 0
	v_mul_f32_e32 v0, v16, v16
	v_pk_mov_b32 v[60:61], v[58:59], v[56:57] op_sel:[1,0]
	v_mov_b32_e32 v59, v57
	v_pk_add_f32 v[56:57], v[60:61], v[58:59]
	v_pk_mul_f32 v[58:59], v[26:27], v[26:27]
	v_pk_mul_f32 v[60:61], v[24:25], v[24:25]
	v_mul_f32_e32 v2, v17, v17
	v_pk_mov_b32 v[62:63], v[60:61], v[58:59] op_sel:[1,0]
	v_mov_b32_e32 v61, v59
	v_pk_add_f32 v[58:59], v[62:63], v[60:61]
	v_pk_add_f32 v[56:57], v[56:57], v[56:57] op_sel:[0,1] op_sel_hi:[1,0]
	v_pk_add_f32 v[58:59], v[58:59], v[58:59] op_sel:[0,1] op_sel_hi:[1,0]
	v_mov_b32_e32 v57, v0
	v_mov_b32_e32 v59, v2
	v_mul_f32_e32 v0, v21, v21
	v_pk_add_f32 v[56:57], v[56:57], v[58:59]
	v_pk_fma_f32 v[58:59], v[20:21], v[20:21], v[0:1] op_sel_hi:[1,1,0]
	v_mul_f32_e32 v0, v23, v23
	v_mul_f32_e32 v4, v18, v18
	v_mul_f32_e32 v6, v19, v19
	v_pk_fma_f32 v[60:61], v[22:23], v[22:23], v[0:1] op_sel_hi:[1,1,0]
	v_mov_b32_e32 v59, v4
	v_mov_b32_e32 v61, v6
	v_pk_add_f32 v[58:59], v[58:59], v[60:61]
	s_nop 0
	v_pk_add_f32 v[56:57], v[56:57], v[58:59]
	s_nop 0
	v_add_f32_e32 v0, v56, v57
	v_lshl_add_u64 v[56:57], v[28:29], 0, v[48:49]
	v_lshl_add_u64 v[60:61], v[56:57], 0, s[6:7]
	v_add_co_u32_e32 v56, vcc, s76, v56
	v_add_f32_dpp v0, v0, v0 quad_perm:[1,0,3,2] row_mask:0xf bank_mask:0xf bound_ctrl:1
	s_nop 0
	v_addc_co_u32_e32 v57, vcc, 0, v57, vcc
	v_mov_b32_e32 v56, v84
	v_mov_b32_e32 v57, v85
	v_mov_b32_e32 v58, v86
	v_mov_b32_e32 v59, v87
	s_nop 0
	v_mov_b32_e32 v60, v88
	v_mov_b32_e32 v61, v89
	v_mov_b32_e32 v62, v90
	v_mov_b32_e32 v63, v91
	v_add_f32_dpp v0, v0, v0 quad_perm:[2,3,0,1] row_mask:0xf bank_mask:0xf bound_ctrl:1
	v_lshl_add_u64 v[48:49], v[48:49], 0, s[60:61]
	s_nop 0
	v_lshlrev_b32_e32 v64, 16, v56
	v_add_f32_dpp v0, v0, v0 row_half_mirror row_mask:0xf bank_mask:0xf bound_ctrl:1
	v_fmamk_f32 v0, v0, 0x3c000000, v194
	v_rsq_f32_e32 v6, v0
	v_mul_f32_e32 v0, 0xbfb8aa3b, v64
	v_exp_f32_e32 v0, v0
	v_mul_f32_e32 v65, v52, v6
	v_and_b32_e32 v52, 0xffff0000, v56
	v_add_f32_e32 v0, 1.0, v0
	v_rcp_f32_e32 v36, v0
	v_mul_f32_e32 v0, 0xbfb8aa3b, v52
	v_exp_f32_e32 v0, v0
	v_mul_f32_e32 v53, v53, v6
	v_mul_f32_e32 v21, v21, v6
	v_mul_f32_e32 v23, v23, v6
	v_add_f32_e32 v0, 1.0, v0
	v_rcp_f32_e32 v8, v0
	v_mul_f32_e32 v27, v27, v6
	v_mul_f32_e32 v19, v19, v6
	v_pk_mul_f32 v[64:65], v[36:37], v[64:65]
	v_pk_mul_f32 v[52:53], v[8:9], v[52:53]
	v_mul_f32_e32 v36, v64, v65
	v_mul_f32_e32 v8, v52, v53
	v_lshlrev_b32_e32 v52, 16, v57
	v_mul_f32_e32 v0, 0xbfb8aa3b, v52
	v_exp_f32_e32 v0, v0
	v_mul_f32_e32 v53, v54, v6
	v_add_f32_e32 v0, 1.0, v0
	v_rcp_f32_e32 v34, v0
	s_nop 0
	v_pk_mul_f32 v[52:53], v[34:35], v[52:53]
	s_nop 0
	v_mul_f32_e32 v34, v52, v53
	v_and_b32_e32 v52, 0xffff0000, v57
	v_mul_f32_e32 v0, 0xbfb8aa3b, v52
	v_exp_f32_e32 v0, v0
; __device__ __forceinline__ float bflo(unsigned w) { return __uint_as_float(w << 16); }
; __device__ __forceinline__ float bfhi(unsigned w) { return __uint_as_float(w & 0xffff0000u); }
; __device__ __forceinline__ float rsq_f(float x) { return __builtin_amdgcn_rsqf(x); }
; __device__ __forceinline__ void onorm_pass(const float* obuf, const bf16_t* z, const float* ong, bf16_t* ycat, int gw, int NGW, int lane) {
;     ...
;     for (int row = gw; row < MP; row += NGW) {
;         const float* op = obuf + (size_t)row * 1024 + lane * 16; const bf16_t* zp = z + (size_t)row * NZ + 7168 + lane * 16;
;         f32x4 v[4]; float ss = 0.f;
; #pragma unroll
;         for (int i = 0; i < 4; ++i) { v[i] = *(const f32x4*)(op + 4 * i); ss += (v[i].x * v[i].x + v[i].y * v[i].y) + (v[i].z * v[i].z + v[i].w * v[i].w); }
;         const u32x4 g0 = *(const u32x4*)zp, g1 = *(const u32x4*)(zp + 8);
;         ss += __builtin_bit_cast(float, __builtin_amdgcn_update_dpp(0, __builtin_bit_cast(int, ss), 0xB1, 0xF, 0xF, true));
;         ss += __builtin_bit_cast(float, __builtin_amdgcn_update_dpp(0, __builtin_bit_cast(int, ss), 0x4E, 0xF, 0xF, true));
;         ss += __builtin_bit_cast(float, __builtin_amdgcn_update_dpp(0, __builtin_bit_cast(int, ss), 0x141, 0xF, 0xF, true));
;         const float rstd = rsq_f(ss * (1.f / HD) + EPS);
;         float y[16];
;         y[0] = v[0].x * rstd * g[0].x * silu_f(bflo(g0.x)); y[1] = v[0].y * rstd * g[0].y * silu_f(bfhi(g0.x)); y[2] = v[0].z * rstd * g[0].z * silu_f(bflo(g0.y)); y[3] = v[0].w * rstd * g[0].w * silu_f(bfhi(g0.y));
;         y[4] = v[1].x * rstd * g[1].x * silu_f(bflo(g0.z)); y[5] = v[1].y * rstd * g[1].y * silu_f(bfhi(g0.z)); y[6] = v[1].z * rstd * g[1].z * silu_f(bflo(g0.w)); y[7] = v[1].w * rstd * g[1].w * silu_f(bfhi(g0.w));
;         y[8] = v[2].x * rstd * g[2].x * silu_f(bflo(g1.x)); y[9] = v[2].y * rstd * g[2].y * silu_f(bfhi(g1.x)); y[10] = v[2].z * rstd * g[2].z * silu_f(bflo(g1.y)); y[11] = v[2].w * rstd * g[2].w * silu_f(bfhi(g1.y));
;         y[12] = v[3].x * rstd * g[3].x * silu_f(bflo(g1.z)); y[13] = v[3].y * rstd * g[3].y * silu_f(bfhi(g1.z)); y[14] = v[3].z * rstd * g[3].z * silu_f(bflo(g1.w)); y[15] = v[3].w * rstd * g[3].w * silu_f(bfhi(g1.w));
;         bf16_t* yp = ycat + (size_t)row * DM + 1024 + lane * 16;
;         *(u32x4*)yp = pack8(y); *(u32x4*)(yp + 8) = pack8(y + 8);
	v_mul_f32_e32 v53, v55, v6
	v_add_f32_e32 v0, 1.0, v0
	v_rcp_f32_e32 v10, v0
	s_nop 0
	v_pk_mul_f32 v[52:53], v[10:11], v[52:53]
	s_nop 0
	v_mul_f32_e32 v10, v52, v53
	v_lshlrev_b32_e32 v52, 16, v58
	v_mul_f32_e32 v0, 0xbfb8aa3b, v52
	v_exp_f32_e32 v0, v0
	v_mul_f32_e32 v53, v24, v6
	v_add_f32_e32 v0, 1.0, v0
	v_rcp_f32_e32 v32, v0
	s_nop 0
	v_pk_mul_f32 v[52:53], v[32:33], v[52:53]
	s_nop 0
	v_mul_f32_e32 v24, v52, v53
	v_and_b32_e32 v52, 0xffff0000, v58
	v_mul_f32_e32 v0, 0xbfb8aa3b, v52
	v_exp_f32_e32 v0, v0
	v_mul_f32_e32 v53, v25, v6
	v_add_f32_e32 v0, 1.0, v0
	v_rcp_f32_e32 v12, v0
	s_nop 0
	v_pk_mul_f32 v[52:53], v[12:13], v[52:53]
	s_nop 0
	v_mul_f32_e32 v12, v52, v53
	v_lshlrev_b32_e32 v52, 16, v59
	v_mul_f32_e32 v0, 0xbfb8aa3b, v52
	v_exp_f32_e32 v0, v0
	v_mul_f32_e32 v53, v26, v6
	v_and_b32_e32 v26, 0xffff0000, v59
	v_cvt_pk_bf16_f32 v24, v24, v12
	v_add_f32_e32 v0, 1.0, v0
	v_rcp_f32_e32 v30, v0
	v_mul_f32_e32 v0, 0xbfb8aa3b, v26
	v_exp_f32_e32 v0, v0
	v_pk_mul_f32 v[52:53], v[30:31], v[52:53]
	s_nop 0
	v_mul_f32_e32 v25, v52, v53
	v_add_f32_e32 v0, 1.0, v0
	s_nop 0
	v_lshlrev_b32_e32 v52, 16, v60
	v_rcp_f32_e32 v14, v0
	v_mul_f32_e32 v0, 0xbfb8aa3b, v52
	v_exp_f32_e32 v0, v0
	v_mul_f32_e32 v53, v20, v6
	v_and_b32_e32 v20, 0xffff0000, v60
	v_pk_mul_f32 v[26:27], v[14:15], v[26:27]
	v_add_f32_e32 v0, 1.0, v0
	v_rcp_f32_e32 v44, v0
	v_mul_f32_e32 v0, 0xbfb8aa3b, v20
	v_exp_f32_e32 v0, v0
	v_mul_f32_e32 v26, v26, v27
	v_cvt_pk_bf16_f32 v25, v25, v26
	v_pk_mul_f32 v[52:53], v[44:45], v[52:53]
	v_add_f32_e32 v0, 1.0, v0
	v_rcp_f32_e32 v0, v0
	v_mul_f32_e32 v14, v52, v53
	v_pk_mul_f32 v[20:21], v[0:1], v[20:21]
	s_nop 0
	v_mul_f32_e32 v0, v20, v21
	v_lshlrev_b32_e32 v20, 16, v61
	v_mul_f32_e32 v2, 0xbfb8aa3b, v20
	v_exp_f32_e32 v2, v2
	v_mul_f32_e32 v21, v22, v6
	v_and_b32_e32 v22, 0xffff0000, v61
	v_add_f32_e32 v2, 1.0, v2
	v_rcp_f32_e32 v42, v2
	v_mul_f32_e32 v2, 0xbfb8aa3b, v22
	v_exp_f32_e32 v2, v2
	v_pk_mul_f32 v[20:21], v[42:43], v[20:21]
	s_nop 0
	v_mul_f32_e32 v20, v20, v21
	v_add_f32_e32 v2, 1.0, v2
	v_rcp_f32_e32 v2, v2
	s_nop 0
	v_pk_mul_f32 v[22:23], v[2:3], v[22:23]
	s_nop 0
	v_mul_f32_e32 v2, v22, v23
	v_lshlrev_b32_e32 v22, 16, v62
	v_mul_f32_e32 v4, 0xbfb8aa3b, v22
	v_exp_f32_e32 v4, v4
	v_mul_f32_e32 v23, v16, v6
	v_add_f32_e32 v4, 1.0, v4
	v_rcp_f32_e32 v40, v4
	s_nop 0
	v_pk_mul_f32 v[22:23], v[40:41], v[22:23]
	s_nop 0
	v_mul_f32_e32 v16, v22, v23
	v_and_b32_e32 v22, 0xffff0000, v62
	v_mul_f32_e32 v4, 0xbfb8aa3b, v22
	v_exp_f32_e32 v4, v4
	v_mul_f32_e32 v23, v17, v6
	v_add_f32_e32 v4, 1.0, v4
	v_rcp_f32_e32 v4, v4
	s_nop 0
	v_pk_mul_f32 v[22:23], v[4:5], v[22:23]
	s_nop 0
	v_mul_f32_e32 v4, v22, v23
	v_mul_f32_e32 v23, v18, v6
	v_and_b32_e32 v18, 0xffff0000, v63
	v_mul_f32_e32 v6, 0xbfb8aa3b, v18
	v_exp_f32_e32 v6, v6
	v_lshlrev_b32_e32 v22, 16, v63
	v_mul_f32_e32 v17, 0xbfb8aa3b, v22
	v_exp_f32_e32 v17, v17
	v_add_f32_e32 v6, 1.0, v6
	v_rcp_f32_e32 v6, v6
	v_add_f32_e32 v17, 1.0, v17
	v_rcp_f32_e32 v38, v17
	v_pk_mul_f32 v[18:19], v[6:7], v[18:19]
	v_pk_mul_f32 v[22:23], v[38:39], v[22:23]
	v_mul_f32_e32 v6, v18, v19
	v_lshl_add_u64 v[18:19], v[28:29], 0, v[46:47]
	v_add_co_u32_e32 v26, vcc, s5, v18
	v_lshl_add_u64 v[46:47], v[46:47], 0, s[84:85]
	s_nop 0
	v_addc_co_u32_e32 v27, vcc, 0, v19, vcc
	v_mul_f32_e32 v17, v22, v23
	v_cvt_pk_bf16_f32 v22, v36, v8
	v_cvt_pk_bf16_f32 v23, v34, v10
	global_store_dwordx4 v[26:27], v[22:25], off offset:2048
	v_cvt_pk_bf16_f32 v18, v14, v0
	v_cvt_pk_bf16_f32 v19, v20, v2
	v_cvt_pk_bf16_f32 v20, v16, v4
	v_cvt_pk_bf16_f32 v21, v17, v6
	global_store_dwordx4 v[26:27], v[18:21], off offset:2064
	global_load_dwordx4 v[68:71], v[200:201], off nt
	global_load_dwordx4 v[72:75], v[200:201], off offset:16 nt
	global_load_dwordx4 v[76:79], v[200:201], off offset:32 nt
	global_load_dwordx4 v[80:83], v[200:201], off offset:48 nt
	global_load_dwordx4 v[84:87], v[202:203], off nt
	global_load_dwordx4 v[88:91], v[202:203], off offset:16 nt
	v_lshl_add_u64 v[200:201], v[200:201], 0, s[84:85]
	v_lshl_add_u64 v[202:203], v[202:203], 0, s[60:61]
	v_lshl_add_u64 v[16:17], v[28:29], 0, v[50:51]
	v_lshl_add_u64 v[18:19], v[16:17], 0, s[8:9]
	v_add_co_u32_e32 v16, vcc, 0x28e00000, v16
	s_mov_b64 s[6:7], 0x13c03800
	s_nop 0
	v_addc_co_u32_e32 v17, vcc, 0, v17, vcc
	s_waitcnt vmcnt(20)
; __device__ __forceinline__ float bflo(unsigned w) { return __uint_as_float(w << 16); }
; __device__ __forceinline__ float bfhi(unsigned w) { return __uint_as_float(w & 0xffff0000u); }
; __device__ __forceinline__ float rsq_f(float x) { return __builtin_amdgcn_rsqf(x); }
; __device__ __forceinline__ void onorm_pass(const float* obuf, const bf16_t* z, const float* ong, bf16_t* ycat, int gw, int NGW, int lane) {
;     ...
;     for (int row = gw; row < MP; row += NGW) {
;         const float* op = obuf + (size_t)row * 1024 + lane * 16; const bf16_t* zp = z + (size_t)row * NZ + 7168 + lane * 16;
;         f32x4 v[4]; float ss = 0.f;
; #pragma unroll
;         for (int i = 0; i < 4; ++i) { v[i] = *(const f32x4*)(op + 4 * i); ss += (v[i].x * v[i].x + v[i].y * v[i].y) + (v[i].z * v[i].z + v[i].w * v[i].w); }
;         const u32x4 g0 = *(const u32x4*)zp, g1 = *(const u32x4*)(zp + 8);
;         ss += __builtin_bit_cast(float, __builtin_amdgcn_update_dpp(0, __builtin_bit_cast(int, ss), 0xB1, 0xF, 0xF, true));
;         ss += __builtin_bit_cast(float, __builtin_amdgcn_update_dpp(0, __builtin_bit_cast(int, ss), 0x4E, 0xF, 0xF, true));
;         ss += __builtin_bit_cast(float, __builtin_amdgcn_update_dpp(0, __builtin_bit_cast(int, ss), 0x141, 0xF, 0xF, true));
;         const float rstd = rsq_f(ss * (1.f / HD) + EPS);
;         float y[16];
;         y[0] = v[0].x * rstd * g[0].x * silu_f(bflo(g0.x)); y[1] = v[0].y * rstd * g[0].y * silu_f(bfhi(g0.x)); y[2] = v[0].z * rstd * g[0].z * silu_f(bflo(g0.y)); y[3] = v[0].w * rstd * g[0].w * silu_f(bfhi(g0.y));
;         y[4] = v[1].x * rstd * g[1].x * silu_f(bflo(g0.z)); y[5] = v[1].y * rstd * g[1].y * silu_f(bfhi(g0.z)); y[6] = v[1].z * rstd * g[1].z * silu_f(bflo(g0.w)); y[7] = v[1].w * rstd * g[1].w * silu_f(bfhi(g0.w));
;         y[8] = v[2].x * rstd * g[2].x * silu_f(bflo(g1.x)); y[9] = v[2].y * rstd * g[2].y * silu_f(bfhi(g1.x)); y[10] = v[2].z * rstd * g[2].z * silu_f(bflo(g1.y)); y[11] = v[2].w * rstd * g[2].w * silu_f(bfhi(g1.y));
;         y[12] = v[3].x * rstd * g[3].x * silu_f(bflo(g1.z)); y[13] = v[3].y * rstd * g[3].y * silu_f(bfhi(g1.z)); y[14] = v[3].z * rstd * g[3].z * silu_f(bflo(g1.w)); y[15] = v[3].w * rstd * g[3].w * silu_f(bfhi(g1.w));
;         bf16_t* yp = ycat + (size_t)row * DM + 1024 + lane * 16;
;         *(u32x4*)yp = pack8(y); *(u32x4*)(yp + 8) = pack8(y + 8);
	v_mov_b32_e32 v52, v92
	v_mov_b32_e32 v53, v93
	v_mov_b32_e32 v54, v94
	v_mov_b32_e32 v55, v95
	v_mov_b32_e32 v20, v100
	v_mov_b32_e32 v21, v101
	v_mov_b32_e32 v22, v102
	v_mov_b32_e32 v23, v103
	v_mov_b32_e32 v24, v96
	v_mov_b32_e32 v25, v97
	v_mov_b32_e32 v26, v98
	v_mov_b32_e32 v27, v99
	s_nop 0
	v_mov_b32_e32 v16, v104
	v_mov_b32_e32 v17, v105
	v_mov_b32_e32 v18, v106
	v_mov_b32_e32 v19, v107
	s_mov_b32 s5, 0x20300000
	s_addk_i32 s4, 0x400
	v_lshl_add_u64 v[50:51], v[50:51], 0, s[84:85]
	s_cmpk_gt_i32 s4, 0x1bff
	s_nop 0
	v_pk_mul_f32 v[56:57], v[54:55], v[54:55]
	v_pk_mul_f32 v[58:59], v[52:53], v[52:53]
	s_nop 0
	v_mul_f32_e32 v0, v16, v16
	v_pk_mov_b32 v[60:61], v[58:59], v[56:57] op_sel:[1,0]
	v_mov_b32_e32 v59, v57
	v_pk_add_f32 v[56:57], v[60:61], v[58:59]
	v_pk_mul_f32 v[58:59], v[26:27], v[26:27]
	v_pk_mul_f32 v[60:61], v[24:25], v[24:25]
	v_mul_f32_e32 v2, v17, v17
	v_pk_mov_b32 v[62:63], v[60:61], v[58:59] op_sel:[1,0]
	v_mov_b32_e32 v61, v59
	v_pk_add_f32 v[58:59], v[62:63], v[60:61]
	v_pk_add_f32 v[56:57], v[56:57], v[56:57] op_sel:[0,1] op_sel_hi:[1,0]
	v_pk_add_f32 v[58:59], v[58:59], v[58:59] op_sel:[0,1] op_sel_hi:[1,0]
	v_mov_b32_e32 v57, v0
	v_mov_b32_e32 v59, v2
	v_mul_f32_e32 v0, v21, v21
	v_pk_add_f32 v[56:57], v[56:57], v[58:59]
	v_pk_fma_f32 v[58:59], v[20:21], v[20:21], v[0:1] op_sel_hi:[1,1,0]
	v_mul_f32_e32 v0, v23, v23
	v_mul_f32_e32 v4, v18, v18
	v_mul_f32_e32 v6, v19, v19
	v_pk_fma_f32 v[60:61], v[22:23], v[22:23], v[0:1] op_sel_hi:[1,1,0]
	v_mov_b32_e32 v59, v4
	v_mov_b32_e32 v61, v6
	v_pk_add_f32 v[58:59], v[58:59], v[60:61]
	s_nop 0
	v_pk_add_f32 v[56:57], v[56:57], v[58:59]
	s_nop 0
	v_add_f32_e32 v0, v56, v57
	v_lshl_add_u64 v[56:57], v[28:29], 0, v[48:49]
	v_lshl_add_u64 v[60:61], v[56:57], 0, s[6:7]
	v_add_co_u32_e32 v56, vcc, s76, v56
	v_add_f32_dpp v0, v0, v0 quad_perm:[1,0,3,2] row_mask:0xf bank_mask:0xf bound_ctrl:1
	s_nop 0
	v_addc_co_u32_e32 v57, vcc, 0, v57, vcc
	v_mov_b32_e32 v56, v108
	v_mov_b32_e32 v57, v109
	v_mov_b32_e32 v58, v110
	v_mov_b32_e32 v59, v111
	s_nop 0
	v_mov_b32_e32 v60, v112
	v_mov_b32_e32 v61, v113
	v_mov_b32_e32 v62, v114
	v_mov_b32_e32 v63, v115
	v_add_f32_dpp v0, v0, v0 quad_perm:[2,3,0,1] row_mask:0xf bank_mask:0xf bound_ctrl:1
	v_lshl_add_u64 v[48:49], v[48:49], 0, s[60:61]
	s_nop 0
	v_lshlrev_b32_e32 v64, 16, v56
	v_add_f32_dpp v0, v0, v0 row_half_mirror row_mask:0xf bank_mask:0xf bound_ctrl:1
	v_fmamk_f32 v0, v0, 0x3c000000, v194
	v_rsq_f32_e32 v6, v0
	v_mul_f32_e32 v0, 0xbfb8aa3b, v64
	v_exp_f32_e32 v0, v0
	v_mul_f32_e32 v65, v52, v6
	v_and_b32_e32 v52, 0xffff0000, v56
	v_add_f32_e32 v0, 1.0, v0
	v_rcp_f32_e32 v36, v0
	v_mul_f32_e32 v0, 0xbfb8aa3b, v52
	v_exp_f32_e32 v0, v0
	v_mul_f32_e32 v53, v53, v6
	v_mul_f32_e32 v21, v21, v6
	v_mul_f32_e32 v23, v23, v6
	v_add_f32_e32 v0, 1.0, v0
	v_rcp_f32_e32 v8, v0
	v_mul_f32_e32 v27, v27, v6
	v_mul_f32_e32 v19, v19, v6
	v_pk_mul_f32 v[64:65], v[36:37], v[64:65]
	v_pk_mul_f32 v[52:53], v[8:9], v[52:53]
	v_mul_f32_e32 v36, v64, v65
	v_mul_f32_e32 v8, v52, v53
	v_lshlrev_b32_e32 v52, 16, v57
	v_mul_f32_e32 v0, 0xbfb8aa3b, v52
	v_exp_f32_e32 v0, v0
	v_mul_f32_e32 v53, v54, v6
	v_add_f32_e32 v0, 1.0, v0
	v_rcp_f32_e32 v34, v0
	s_nop 0
	v_pk_mul_f32 v[52:53], v[34:35], v[52:53]
	s_nop 0
	v_mul_f32_e32 v34, v52, v53
	v_and_b32_e32 v52, 0xffff0000, v57
	v_mul_f32_e32 v0, 0xbfb8aa3b, v52
	v_exp_f32_e32 v0, v0
	v_mul_f32_e32 v53, v55, v6
	v_add_f32_e32 v0, 1.0, v0
	v_rcp_f32_e32 v10, v0
	s_nop 0
	v_pk_mul_f32 v[52:53], v[10:11], v[52:53]
	s_nop 0
	v_mul_f32_e32 v10, v52, v53
	v_lshlrev_b32_e32 v52, 16, v58
	v_mul_f32_e32 v0, 0xbfb8aa3b, v52
	v_exp_f32_e32 v0, v0
	v_mul_f32_e32 v53, v24, v6
	v_add_f32_e32 v0, 1.0, v0
	v_rcp_f32_e32 v32, v0
	s_nop 0
	v_pk_mul_f32 v[52:53], v[32:33], v[52:53]
	s_nop 0
	v_mul_f32_e32 v24, v52, v53
	v_and_b32_e32 v52, 0xffff0000, v58
	v_mul_f32_e32 v0, 0xbfb8aa3b, v52
	v_exp_f32_e32 v0, v0
	v_mul_f32_e32 v53, v25, v6
	v_add_f32_e32 v0, 1.0, v0
	v_rcp_f32_e32 v12, v0
	s_nop 0
	v_pk_mul_f32 v[52:53], v[12:13], v[52:53]
	s_nop 0
	v_mul_f32_e32 v12, v52, v53
	v_lshlrev_b32_e32 v52, 16, v59
	v_mul_f32_e32 v0, 0xbfb8aa3b, v52
	v_exp_f32_e32 v0, v0
	v_mul_f32_e32 v53, v26, v6
	v_and_b32_e32 v26, 0xffff0000, v59
	v_cvt_pk_bf16_f32 v24, v24, v12
	v_add_f32_e32 v0, 1.0, v0
	v_rcp_f32_e32 v30, v0
	v_mul_f32_e32 v0, 0xbfb8aa3b, v26
	v_exp_f32_e32 v0, v0
	v_pk_mul_f32 v[52:53], v[30:31], v[52:53]
	s_nop 0
	v_mul_f32_e32 v25, v52, v53
	v_add_f32_e32 v0, 1.0, v0
	s_nop 0
	v_lshlrev_b32_e32 v52, 16, v60
	v_rcp_f32_e32 v14, v0
	v_mul_f32_e32 v0, 0xbfb8aa3b, v52
	v_exp_f32_e32 v0, v0
	v_mul_f32_e32 v53, v20, v6
	v_and_b32_e32 v20, 0xffff0000, v60
	v_pk_mul_f32 v[26:27], v[14:15], v[26:27]
	v_add_f32_e32 v0, 1.0, v0
	v_rcp_f32_e32 v44, v0
	v_mul_f32_e32 v0, 0xbfb8aa3b, v20
	v_exp_f32_e32 v0, v0
	v_mul_f32_e32 v26, v26, v27
	v_cvt_pk_bf16_f32 v25, v25, v26
	v_pk_mul_f32 v[52:53], v[44:45], v[52:53]
	v_add_f32_e32 v0, 1.0, v0
	v_rcp_f32_e32 v0, v0
	v_mul_f32_e32 v14, v52, v53
	v_pk_mul_f32 v[20:21], v[0:1], v[20:21]
	s_nop 0
	v_mul_f32_e32 v0, v20, v21
	v_lshlrev_b32_e32 v20, 16, v61
	v_mul_f32_e32 v2, 0xbfb8aa3b, v20
	v_exp_f32_e32 v2, v2
	v_mul_f32_e32 v21, v22, v6
	v_and_b32_e32 v22, 0xffff0000, v61
	v_add_f32_e32 v2, 1.0, v2
	v_rcp_f32_e32 v42, v2
	v_mul_f32_e32 v2, 0xbfb8aa3b, v22
	v_exp_f32_e32 v2, v2
	v_pk_mul_f32 v[20:21], v[42:43], v[20:21]
	s_nop 0
	v_mul_f32_e32 v20, v20, v21
	v_add_f32_e32 v2, 1.0, v2
	v_rcp_f32_e32 v2, v2
	s_nop 0
	v_pk_mul_f32 v[22:23], v[2:3], v[22:23]
	s_nop 0
	v_mul_f32_e32 v2, v22, v23
	v_lshlrev_b32_e32 v22, 16, v62
	v_mul_f32_e32 v4, 0xbfb8aa3b, v22
	v_exp_f32_e32 v4, v4
; __device__ __forceinline__ float bflo(unsigned w) { return __uint_as_float(w << 16); }
; __device__ __forceinline__ float bfhi(unsigned w) { return __uint_as_float(w & 0xffff0000u); }
; __device__ __forceinline__ float rsq_f(float x) { return __builtin_amdgcn_rsqf(x); }
; __device__ __forceinline__ void onorm_pass(const float* obuf, const bf16_t* z, const float* ong, bf16_t* ycat, int gw, int NGW, int lane) {
;     ...
;     for (int row = gw; row < MP; row += NGW) {
;         const float* op = obuf + (size_t)row * 1024 + lane * 16; const bf16_t* zp = z + (size_t)row * NZ + 7168 + lane * 16;
;         f32x4 v[4]; float ss = 0.f;
; #pragma unroll
;         for (int i = 0; i < 4; ++i) { v[i] = *(const f32x4*)(op + 4 * i); ss += (v[i].x * v[i].x + v[i].y * v[i].y) + (v[i].z * v[i].z + v[i].w * v[i].w); }
;         const u32x4 g0 = *(const u32x4*)zp, g1 = *(const u32x4*)(zp + 8);
;         ss += __builtin_bit_cast(float, __builtin_amdgcn_update_dpp(0, __builtin_bit_cast(int, ss), 0xB1, 0xF, 0xF, true));
;         ss += __builtin_bit_cast(float, __builtin_amdgcn_update_dpp(0, __builtin_bit_cast(int, ss), 0x4E, 0xF, 0xF, true));
;         ss += __builtin_bit_cast(float, __builtin_amdgcn_update_dpp(0, __builtin_bit_cast(int, ss), 0x141, 0xF, 0xF, true));
;         const float rstd = rsq_f(ss * (1.f / HD) + EPS);
;         float y[16];
;         y[0] = v[0].x * rstd * g[0].x * silu_f(bflo(g0.x)); y[1] = v[0].y * rstd * g[0].y * silu_f(bfhi(g0.x)); y[2] = v[0].z * rstd * g[0].z * silu_f(bflo(g0.y)); y[3] = v[0].w * rstd * g[0].w * silu_f(bfhi(g0.y));
;         y[4] = v[1].x * rstd * g[1].x * silu_f(bflo(g0.z)); y[5] = v[1].y * rstd * g[1].y * silu_f(bfhi(g0.z)); y[6] = v[1].z * rstd * g[1].z * silu_f(bflo(g0.w)); y[7] = v[1].w * rstd * g[1].w * silu_f(bfhi(g0.w));
;         y[8] = v[2].x * rstd * g[2].x * silu_f(bflo(g1.x)); y[9] = v[2].y * rstd * g[2].y * silu_f(bfhi(g1.x)); y[10] = v[2].z * rstd * g[2].z * silu_f(bflo(g1.y)); y[11] = v[2].w * rstd * g[2].w * silu_f(bfhi(g1.y));
;         y[12] = v[3].x * rstd * g[3].x * silu_f(bflo(g1.z)); y[13] = v[3].y * rstd * g[3].y * silu_f(bfhi(g1.z)); y[14] = v[3].z * rstd * g[3].z * silu_f(bflo(g1.w)); y[15] = v[3].w * rstd * g[3].w * silu_f(bfhi(g1.w));
;         bf16_t* yp = ycat + (size_t)row * DM + 1024 + lane * 16;
;         *(u32x4*)yp = pack8(y); *(u32x4*)(yp + 8) = pack8(y + 8);
	v_mul_f32_e32 v23, v16, v6
	v_add_f32_e32 v4, 1.0, v4
	v_rcp_f32_e32 v40, v4
	s_nop 0
	v_pk_mul_f32 v[22:23], v[40:41], v[22:23]
	s_nop 0
	v_mul_f32_e32 v16, v22, v23
	v_and_b32_e32 v22, 0xffff0000, v62
	v_mul_f32_e32 v4, 0xbfb8aa3b, v22
	v_exp_f32_e32 v4, v4
	v_mul_f32_e32 v23, v17, v6
	v_add_f32_e32 v4, 1.0, v4
	v_rcp_f32_e32 v4, v4
	s_nop 0
	v_pk_mul_f32 v[22:23], v[4:5], v[22:23]
	s_nop 0
	v_mul_f32_e32 v4, v22, v23
	v_mul_f32_e32 v23, v18, v6
	v_and_b32_e32 v18, 0xffff0000, v63
	v_mul_f32_e32 v6, 0xbfb8aa3b, v18
	v_exp_f32_e32 v6, v6
	v_lshlrev_b32_e32 v22, 16, v63
	v_mul_f32_e32 v17, 0xbfb8aa3b, v22
	v_exp_f32_e32 v17, v17
	v_add_f32_e32 v6, 1.0, v6
	v_rcp_f32_e32 v6, v6
	v_add_f32_e32 v17, 1.0, v17
	v_rcp_f32_e32 v38, v17
	v_pk_mul_f32 v[18:19], v[6:7], v[18:19]
	v_pk_mul_f32 v[22:23], v[38:39], v[22:23]
	v_mul_f32_e32 v6, v18, v19
	v_lshl_add_u64 v[18:19], v[28:29], 0, v[46:47]
	v_add_co_u32_e32 v26, vcc, s5, v18
	v_lshl_add_u64 v[46:47], v[46:47], 0, s[84:85]
	s_nop 0
	v_addc_co_u32_e32 v27, vcc, 0, v19, vcc
	v_mul_f32_e32 v17, v22, v23
	v_cvt_pk_bf16_f32 v22, v36, v8
	v_cvt_pk_bf16_f32 v23, v34, v10
	global_store_dwordx4 v[26:27], v[22:25], off offset:2048
	v_cvt_pk_bf16_f32 v18, v14, v0
	v_cvt_pk_bf16_f32 v19, v20, v2
	v_cvt_pk_bf16_f32 v20, v16, v4
	v_cvt_pk_bf16_f32 v21, v17, v6
	global_store_dwordx4 v[26:27], v[18:21], off offset:2064
	global_load_dwordx4 v[92:95], v[200:201], off nt
	global_load_dwordx4 v[96:99], v[200:201], off offset:16 nt
	global_load_dwordx4 v[100:103], v[200:201], off offset:32 nt
	global_load_dwordx4 v[104:107], v[200:201], off offset:48 nt
	global_load_dwordx4 v[108:111], v[202:203], off nt
	global_load_dwordx4 v[112:115], v[202:203], off offset:16 nt
	v_lshl_add_u64 v[200:201], v[200:201], 0, s[84:85]
	v_lshl_add_u64 v[202:203], v[202:203], 0, s[60:61]
	v_lshl_add_u64 v[16:17], v[28:29], 0, v[50:51]
	v_lshl_add_u64 v[18:19], v[16:17], 0, s[8:9]
	v_add_co_u32_e32 v16, vcc, 0x28e00000, v16
	s_mov_b64 s[6:7], 0x13c03800
	s_nop 0
	v_addc_co_u32_e32 v17, vcc, 0, v17, vcc
	s_waitcnt vmcnt(22)
	v_mov_b32_e32 v52, v116
	v_mov_b32_e32 v53, v117
	v_mov_b32_e32 v54, v118
	v_mov_b32_e32 v55, v119
	v_mov_b32_e32 v20, v124
	v_mov_b32_e32 v21, v125
	v_mov_b32_e32 v22, v126
	v_mov_b32_e32 v23, v127
	v_mov_b32_e32 v24, v120
	v_mov_b32_e32 v25, v121
	v_mov_b32_e32 v26, v122
	v_mov_b32_e32 v27, v123
	s_nop 0
	v_mov_b32_e32 v16, v128
	v_mov_b32_e32 v17, v129
	v_mov_b32_e32 v18, v130
	v_mov_b32_e32 v19, v131
	s_mov_b32 s5, 0x20300000
	s_addk_i32 s4, 0x400
	v_lshl_add_u64 v[50:51], v[50:51], 0, s[84:85]
	s_cmpk_gt_i32 s4, 0x1bff
	s_nop 0
	v_pk_mul_f32 v[56:57], v[54:55], v[54:55]
	v_pk_mul_f32 v[58:59], v[52:53], v[52:53]
	s_nop 0
	v_mul_f32_e32 v0, v16, v16
	v_pk_mov_b32 v[60:61], v[58:59], v[56:57] op_sel:[1,0]
	v_mov_b32_e32 v59, v57
	v_pk_add_f32 v[56:57], v[60:61], v[58:59]
	v_pk_mul_f32 v[58:59], v[26:27], v[26:27]
	v_pk_mul_f32 v[60:61], v[24:25], v[24:25]
	v_mul_f32_e32 v2, v17, v17
	v_pk_mov_b32 v[62:63], v[60:61], v[58:59] op_sel:[1,0]
	v_mov_b32_e32 v61, v59
	v_pk_add_f32 v[58:59], v[62:63], v[60:61]
	v_pk_add_f32 v[56:57], v[56:57], v[56:57] op_sel:[0,1] op_sel_hi:[1,0]
	v_pk_add_f32 v[58:59], v[58:59], v[58:59] op_sel:[0,1] op_sel_hi:[1,0]
	v_mov_b32_e32 v57, v0
	v_mov_b32_e32 v59, v2
	v_mul_f32_e32 v0, v21, v21
	v_pk_add_f32 v[56:57], v[56:57], v[58:59]
	v_pk_fma_f32 v[58:59], v[20:21], v[20:21], v[0:1] op_sel_hi:[1,1,0]
	v_mul_f32_e32 v0, v23, v23
	v_mul_f32_e32 v4, v18, v18
	v_mul_f32_e32 v6, v19, v19
	v_pk_fma_f32 v[60:61], v[22:23], v[22:23], v[0:1] op_sel_hi:[1,1,0]
	v_mov_b32_e32 v59, v4
	v_mov_b32_e32 v61, v6
	v_pk_add_f32 v[58:59], v[58:59], v[60:61]
	s_nop 0
	v_pk_add_f32 v[56:57], v[56:57], v[58:59]
	s_nop 0
	v_add_f32_e32 v0, v56, v57
	v_lshl_add_u64 v[56:57], v[28:29], 0, v[48:49]
	v_lshl_add_u64 v[60:61], v[56:57], 0, s[6:7]
	v_add_co_u32_e32 v56, vcc, s76, v56
	v_add_f32_dpp v0, v0, v0 quad_perm:[1,0,3,2] row_mask:0xf bank_mask:0xf bound_ctrl:1
	s_nop 0
	v_addc_co_u32_e32 v57, vcc, 0, v57, vcc
	v_mov_b32_e32 v56, v132
	v_mov_b32_e32 v57, v133
	v_mov_b32_e32 v58, v134
	v_mov_b32_e32 v59, v135
	s_nop 0
	v_mov_b32_e32 v60, v136
	v_mov_b32_e32 v61, v137
	v_mov_b32_e32 v62, v138
	v_mov_b32_e32 v63, v139
	v_add_f32_dpp v0, v0, v0 quad_perm:[2,3,0,1] row_mask:0xf bank_mask:0xf bound_ctrl:1
	v_lshl_add_u64 v[48:49], v[48:49], 0, s[60:61]
	s_nop 0
	v_lshlrev_b32_e32 v64, 16, v56
	v_add_f32_dpp v0, v0, v0 row_half_mirror row_mask:0xf bank_mask:0xf bound_ctrl:1
	v_fmamk_f32 v0, v0, 0x3c000000, v194
	v_rsq_f32_e32 v6, v0
	v_mul_f32_e32 v0, 0xbfb8aa3b, v64
	v_exp_f32_e32 v0, v0
	v_mul_f32_e32 v65, v52, v6
	v_and_b32_e32 v52, 0xffff0000, v56
	v_add_f32_e32 v0, 1.0, v0
	v_rcp_f32_e32 v36, v0
	v_mul_f32_e32 v0, 0xbfb8aa3b, v52
	v_exp_f32_e32 v0, v0
	v_mul_f32_e32 v53, v53, v6
	v_mul_f32_e32 v21, v21, v6
	v_mul_f32_e32 v23, v23, v6
	v_add_f32_e32 v0, 1.0, v0
	v_rcp_f32_e32 v8, v0
	v_mul_f32_e32 v27, v27, v6
	v_mul_f32_e32 v19, v19, v6
	v_pk_mul_f32 v[64:65], v[36:37], v[64:65]
	v_pk_mul_f32 v[52:53], v[8:9], v[52:53]
	v_mul_f32_e32 v36, v64, v65
	v_mul_f32_e32 v8, v52, v53
	v_lshlrev_b32_e32 v52, 16, v57
	v_mul_f32_e32 v0, 0xbfb8aa3b, v52
	v_exp_f32_e32 v0, v0
	v_mul_f32_e32 v53, v54, v6
	v_add_f32_e32 v0, 1.0, v0
	v_rcp_f32_e32 v34, v0
	s_nop 0
	v_pk_mul_f32 v[52:53], v[34:35], v[52:53]
	s_nop 0
	v_mul_f32_e32 v34, v52, v53
	v_and_b32_e32 v52, 0xffff0000, v57
	v_mul_f32_e32 v0, 0xbfb8aa3b, v52
	v_exp_f32_e32 v0, v0
	v_mul_f32_e32 v53, v55, v6
	v_add_f32_e32 v0, 1.0, v0
	v_rcp_f32_e32 v10, v0
	s_nop 0
	v_pk_mul_f32 v[52:53], v[10:11], v[52:53]
	s_nop 0
	v_mul_f32_e32 v10, v52, v53
	v_lshlrev_b32_e32 v52, 16, v58
; __device__ __forceinline__ float bflo(unsigned w) { return __uint_as_float(w << 16); }
; __device__ __forceinline__ float bfhi(unsigned w) { return __uint_as_float(w & 0xffff0000u); }
; __device__ __forceinline__ float rsq_f(float x) { return __builtin_amdgcn_rsqf(x); }
; __device__ __forceinline__ void onorm_pass(const float* obuf, const bf16_t* z, const float* ong, bf16_t* ycat, int gw, int NGW, int lane) {
;     ...
;     for (int row = gw; row < MP; row += NGW) {
;         const float* op = obuf + (size_t)row * 1024 + lane * 16; const bf16_t* zp = z + (size_t)row * NZ + 7168 + lane * 16;
;         f32x4 v[4]; float ss = 0.f;
; #pragma unroll
;         for (int i = 0; i < 4; ++i) { v[i] = *(const f32x4*)(op + 4 * i); ss += (v[i].x * v[i].x + v[i].y * v[i].y) + (v[i].z * v[i].z + v[i].w * v[i].w); }
;         const u32x4 g0 = *(const u32x4*)zp, g1 = *(const u32x4*)(zp + 8);
;         ss += __builtin_bit_cast(float, __builtin_amdgcn_update_dpp(0, __builtin_bit_cast(int, ss), 0xB1, 0xF, 0xF, true));
;         ss += __builtin_bit_cast(float, __builtin_amdgcn_update_dpp(0, __builtin_bit_cast(int, ss), 0x4E, 0xF, 0xF, true));
;         ss += __builtin_bit_cast(float, __builtin_amdgcn_update_dpp(0, __builtin_bit_cast(int, ss), 0x141, 0xF, 0xF, true));
;         const float rstd = rsq_f(ss * (1.f / HD) + EPS);
;         float y[16];
;         y[0] = v[0].x * rstd * g[0].x * silu_f(bflo(g0.x)); y[1] = v[0].y * rstd * g[0].y * silu_f(bfhi(g0.x)); y[2] = v[0].z * rstd * g[0].z * silu_f(bflo(g0.y)); y[3] = v[0].w * rstd * g[0].w * silu_f(bfhi(g0.y));
;         y[4] = v[1].x * rstd * g[1].x * silu_f(bflo(g0.z)); y[5] = v[1].y * rstd * g[1].y * silu_f(bfhi(g0.z)); y[6] = v[1].z * rstd * g[1].z * silu_f(bflo(g0.w)); y[7] = v[1].w * rstd * g[1].w * silu_f(bfhi(g0.w));
;         y[8] = v[2].x * rstd * g[2].x * silu_f(bflo(g1.x)); y[9] = v[2].y * rstd * g[2].y * silu_f(bfhi(g1.x)); y[10] = v[2].z * rstd * g[2].z * silu_f(bflo(g1.y)); y[11] = v[2].w * rstd * g[2].w * silu_f(bfhi(g1.y));
;         y[12] = v[3].x * rstd * g[3].x * silu_f(bflo(g1.z)); y[13] = v[3].y * rstd * g[3].y * silu_f(bfhi(g1.z)); y[14] = v[3].z * rstd * g[3].z * silu_f(bflo(g1.w)); y[15] = v[3].w * rstd * g[3].w * silu_f(bfhi(g1.w));
;         bf16_t* yp = ycat + (size_t)row * DM + 1024 + lane * 16;
;         *(u32x4*)yp = pack8(y); *(u32x4*)(yp + 8) = pack8(y + 8);
	v_mul_f32_e32 v0, 0xbfb8aa3b, v52
	v_exp_f32_e32 v0, v0
	v_mul_f32_e32 v53, v24, v6
	v_add_f32_e32 v0, 1.0, v0
	v_rcp_f32_e32 v32, v0
	s_nop 0
	v_pk_mul_f32 v[52:53], v[32:33], v[52:53]
	s_nop 0
	v_mul_f32_e32 v24, v52, v53
	v_and_b32_e32 v52, 0xffff0000, v58
	v_mul_f32_e32 v0, 0xbfb8aa3b, v52
	v_exp_f32_e32 v0, v0
	v_mul_f32_e32 v53, v25, v6
	v_add_f32_e32 v0, 1.0, v0
	v_rcp_f32_e32 v12, v0
	s_nop 0
	v_pk_mul_f32 v[52:53], v[12:13], v[52:53]
	s_nop 0
	v_mul_f32_e32 v12, v52, v53
	v_lshlrev_b32_e32 v52, 16, v59
	v_mul_f32_e32 v0, 0xbfb8aa3b, v52
	v_exp_f32_e32 v0, v0
	v_mul_f32_e32 v53, v26, v6
	v_and_b32_e32 v26, 0xffff0000, v59
	v_cvt_pk_bf16_f32 v24, v24, v12
	v_add_f32_e32 v0, 1.0, v0
	v_rcp_f32_e32 v30, v0
	v_mul_f32_e32 v0, 0xbfb8aa3b, v26
	v_exp_f32_e32 v0, v0
	v_pk_mul_f32 v[52:53], v[30:31], v[52:53]
	s_nop 0
	v_mul_f32_e32 v25, v52, v53
	v_add_f32_e32 v0, 1.0, v0
	s_nop 0
	v_lshlrev_b32_e32 v52, 16, v60
	v_rcp_f32_e32 v14, v0
	v_mul_f32_e32 v0, 0xbfb8aa3b, v52
	v_exp_f32_e32 v0, v0
	v_mul_f32_e32 v53, v20, v6
	v_and_b32_e32 v20, 0xffff0000, v60
	v_pk_mul_f32 v[26:27], v[14:15], v[26:27]
	v_add_f32_e32 v0, 1.0, v0
	v_rcp_f32_e32 v44, v0
	v_mul_f32_e32 v0, 0xbfb8aa3b, v20
	v_exp_f32_e32 v0, v0
	v_mul_f32_e32 v26, v26, v27
	v_cvt_pk_bf16_f32 v25, v25, v26
	v_pk_mul_f32 v[52:53], v[44:45], v[52:53]
	v_add_f32_e32 v0, 1.0, v0
	v_rcp_f32_e32 v0, v0
	v_mul_f32_e32 v14, v52, v53
	v_pk_mul_f32 v[20:21], v[0:1], v[20:21]
	s_nop 0
	v_mul_f32_e32 v0, v20, v21
	v_lshlrev_b32_e32 v20, 16, v61
	v_mul_f32_e32 v2, 0xbfb8aa3b, v20
	v_exp_f32_e32 v2, v2
	v_mul_f32_e32 v21, v22, v6
	v_and_b32_e32 v22, 0xffff0000, v61
	v_add_f32_e32 v2, 1.0, v2
	v_rcp_f32_e32 v42, v2
	v_mul_f32_e32 v2, 0xbfb8aa3b, v22
	v_exp_f32_e32 v2, v2
	v_pk_mul_f32 v[20:21], v[42:43], v[20:21]
	s_nop 0
	v_mul_f32_e32 v20, v20, v21
	v_add_f32_e32 v2, 1.0, v2
	v_rcp_f32_e32 v2, v2
	s_nop 0
	v_pk_mul_f32 v[22:23], v[2:3], v[22:23]
	s_nop 0
	v_mul_f32_e32 v2, v22, v23
	v_lshlrev_b32_e32 v22, 16, v62
	v_mul_f32_e32 v4, 0xbfb8aa3b, v22
	v_exp_f32_e32 v4, v4
	v_mul_f32_e32 v23, v16, v6
	v_add_f32_e32 v4, 1.0, v4
	v_rcp_f32_e32 v40, v4
	s_nop 0
	v_pk_mul_f32 v[22:23], v[40:41], v[22:23]
	s_nop 0
	v_mul_f32_e32 v16, v22, v23
	v_and_b32_e32 v22, 0xffff0000, v62
	v_mul_f32_e32 v4, 0xbfb8aa3b, v22
	v_exp_f32_e32 v4, v4
	v_mul_f32_e32 v23, v17, v6
	v_add_f32_e32 v4, 1.0, v4
	v_rcp_f32_e32 v4, v4
	s_nop 0
	v_pk_mul_f32 v[22:23], v[4:5], v[22:23]
	s_nop 0
	v_mul_f32_e32 v4, v22, v23
	v_mul_f32_e32 v23, v18, v6
	v_and_b32_e32 v18, 0xffff0000, v63
	v_mul_f32_e32 v6, 0xbfb8aa3b, v18
	v_exp_f32_e32 v6, v6
	v_lshlrev_b32_e32 v22, 16, v63
	v_mul_f32_e32 v17, 0xbfb8aa3b, v22
	v_exp_f32_e32 v17, v17
	v_add_f32_e32 v6, 1.0, v6
	v_rcp_f32_e32 v6, v6
	v_add_f32_e32 v17, 1.0, v17
	v_rcp_f32_e32 v38, v17
	v_pk_mul_f32 v[18:19], v[6:7], v[18:19]
	v_pk_mul_f32 v[22:23], v[38:39], v[22:23]
	v_mul_f32_e32 v6, v18, v19
	v_lshl_add_u64 v[18:19], v[28:29], 0, v[46:47]
	v_add_co_u32_e32 v26, vcc, s5, v18
	v_lshl_add_u64 v[46:47], v[46:47], 0, s[84:85]
	s_nop 0
	v_addc_co_u32_e32 v27, vcc, 0, v19, vcc
	v_mul_f32_e32 v17, v22, v23
	v_cvt_pk_bf16_f32 v22, v36, v8
	v_cvt_pk_bf16_f32 v23, v34, v10
	global_store_dwordx4 v[26:27], v[22:25], off offset:2048
	v_cvt_pk_bf16_f32 v18, v14, v0
	v_cvt_pk_bf16_f32 v19, v20, v2
	v_cvt_pk_bf16_f32 v20, v16, v4
	v_cvt_pk_bf16_f32 v21, v17, v6
	global_store_dwordx4 v[26:27], v[18:21], off offset:2064
	global_load_dwordx4 v[116:119], v[200:201], off nt
	global_load_dwordx4 v[120:123], v[200:201], off offset:16 nt
	global_load_dwordx4 v[124:127], v[200:201], off offset:32 nt
	global_load_dwordx4 v[128:131], v[200:201], off offset:48 nt
	global_load_dwordx4 v[132:135], v[202:203], off nt
	global_load_dwordx4 v[136:139], v[202:203], off offset:16 nt
	v_lshl_add_u64 v[200:201], v[200:201], 0, s[84:85]
	v_lshl_add_u64 v[202:203], v[202:203], 0, s[60:61]
	v_lshl_add_u64 v[16:17], v[28:29], 0, v[50:51]
	v_lshl_add_u64 v[18:19], v[16:17], 0, s[8:9]
	v_add_co_u32_e32 v16, vcc, 0x28e00000, v16
	s_mov_b64 s[6:7], 0x13c03800
	s_nop 0
	v_addc_co_u32_e32 v17, vcc, 0, v17, vcc
	s_waitcnt vmcnt(24)
	v_mov_b32_e32 v52, v140
	v_mov_b32_e32 v53, v141
	v_mov_b32_e32 v54, v142
	v_mov_b32_e32 v55, v143
	v_mov_b32_e32 v20, v148
	v_mov_b32_e32 v21, v149
	v_mov_b32_e32 v22, v150
	v_mov_b32_e32 v23, v151
	v_mov_b32_e32 v24, v144
	v_mov_b32_e32 v25, v145
	v_mov_b32_e32 v26, v146
	v_mov_b32_e32 v27, v147
	s_nop 0
	v_mov_b32_e32 v16, v156
	v_mov_b32_e32 v17, v157
	v_mov_b32_e32 v18, v158
	v_mov_b32_e32 v19, v159
	s_mov_b32 s5, 0x20300000
	s_addk_i32 s4, 0x400
	v_lshl_add_u64 v[50:51], v[50:51], 0, s[84:85]
	s_cmpk_gt_i32 s4, 0x1bff
	s_nop 0
	v_pk_mul_f32 v[56:57], v[54:55], v[54:55]
	v_pk_mul_f32 v[58:59], v[52:53], v[52:53]
	s_nop 0
	v_mul_f32_e32 v0, v16, v16
	v_pk_mov_b32 v[60:61], v[58:59], v[56:57] op_sel:[1,0]
	v_mov_b32_e32 v59, v57
	v_pk_add_f32 v[56:57], v[60:61], v[58:59]
	v_pk_mul_f32 v[58:59], v[26:27], v[26:27]
	v_pk_mul_f32 v[60:61], v[24:25], v[24:25]
	v_mul_f32_e32 v2, v17, v17
	v_pk_mov_b32 v[62:63], v[60:61], v[58:59] op_sel:[1,0]
	v_mov_b32_e32 v61, v59
	v_pk_add_f32 v[58:59], v[62:63], v[60:61]
	v_pk_add_f32 v[56:57], v[56:57], v[56:57] op_sel:[0,1] op_sel_hi:[1,0]
	v_pk_add_f32 v[58:59], v[58:59], v[58:59] op_sel:[0,1] op_sel_hi:[1,0]
	v_mov_b32_e32 v57, v0
	v_mov_b32_e32 v59, v2
	v_mul_f32_e32 v0, v21, v21
	v_pk_add_f32 v[56:57], v[56:57], v[58:59]
	v_pk_fma_f32 v[58:59], v[20:21], v[20:21], v[0:1] op_sel_hi:[1,1,0]
	v_mul_f32_e32 v0, v23, v23
	v_mul_f32_e32 v4, v18, v18
	v_mul_f32_e32 v6, v19, v19
	v_pk_fma_f32 v[60:61], v[22:23], v[22:23], v[0:1] op_sel_hi:[1,1,0]
	v_mov_b32_e32 v59, v4
; __device__ __forceinline__ float bflo(unsigned w) { return __uint_as_float(w << 16); }
; __device__ __forceinline__ float bfhi(unsigned w) { return __uint_as_float(w & 0xffff0000u); }
; __device__ __forceinline__ float rsq_f(float x) { return __builtin_amdgcn_rsqf(x); }
; __device__ __forceinline__ void onorm_pass(const float* obuf, const bf16_t* z, const float* ong, bf16_t* ycat, int gw, int NGW, int lane) {
;     ...
;     for (int row = gw; row < MP; row += NGW) {
;         const float* op = obuf + (size_t)row * 1024 + lane * 16; const bf16_t* zp = z + (size_t)row * NZ + 7168 + lane * 16;
;         f32x4 v[4]; float ss = 0.f;
; #pragma unroll
;         for (int i = 0; i < 4; ++i) { v[i] = *(const f32x4*)(op + 4 * i); ss += (v[i].x * v[i].x + v[i].y * v[i].y) + (v[i].z * v[i].z + v[i].w * v[i].w); }
;         const u32x4 g0 = *(const u32x4*)zp, g1 = *(const u32x4*)(zp + 8);
;         ss += __builtin_bit_cast(float, __builtin_amdgcn_update_dpp(0, __builtin_bit_cast(int, ss), 0xB1, 0xF, 0xF, true));
;         ss += __builtin_bit_cast(float, __builtin_amdgcn_update_dpp(0, __builtin_bit_cast(int, ss), 0x4E, 0xF, 0xF, true));
;         ss += __builtin_bit_cast(float, __builtin_amdgcn_update_dpp(0, __builtin_bit_cast(int, ss), 0x141, 0xF, 0xF, true));
;         const float rstd = rsq_f(ss * (1.f / HD) + EPS);
;         float y[16];
;         y[0] = v[0].x * rstd * g[0].x * silu_f(bflo(g0.x)); y[1] = v[0].y * rstd * g[0].y * silu_f(bfhi(g0.x)); y[2] = v[0].z * rstd * g[0].z * silu_f(bflo(g0.y)); y[3] = v[0].w * rstd * g[0].w * silu_f(bfhi(g0.y));
;         y[4] = v[1].x * rstd * g[1].x * silu_f(bflo(g0.z)); y[5] = v[1].y * rstd * g[1].y * silu_f(bfhi(g0.z)); y[6] = v[1].z * rstd * g[1].z * silu_f(bflo(g0.w)); y[7] = v[1].w * rstd * g[1].w * silu_f(bfhi(g0.w));
;         y[8] = v[2].x * rstd * g[2].x * silu_f(bflo(g1.x)); y[9] = v[2].y * rstd * g[2].y * silu_f(bfhi(g1.x)); y[10] = v[2].z * rstd * g[2].z * silu_f(bflo(g1.y)); y[11] = v[2].w * rstd * g[2].w * silu_f(bfhi(g1.y));
;         y[12] = v[3].x * rstd * g[3].x * silu_f(bflo(g1.z)); y[13] = v[3].y * rstd * g[3].y * silu_f(bfhi(g1.z)); y[14] = v[3].z * rstd * g[3].z * silu_f(bflo(g1.w)); y[15] = v[3].w * rstd * g[3].w * silu_f(bfhi(g1.w));
;         bf16_t* yp = ycat + (size_t)row * DM + 1024 + lane * 16;
;         *(u32x4*)yp = pack8(y); *(u32x4*)(yp + 8) = pack8(y + 8);
	v_mov_b32_e32 v61, v6
	v_pk_add_f32 v[58:59], v[58:59], v[60:61]
	s_nop 0
	v_pk_add_f32 v[56:57], v[56:57], v[58:59]
	s_nop 0
	v_add_f32_e32 v0, v56, v57
	v_lshl_add_u64 v[56:57], v[28:29], 0, v[48:49]
	v_lshl_add_u64 v[60:61], v[56:57], 0, s[6:7]
	v_add_co_u32_e32 v56, vcc, s76, v56
	v_add_f32_dpp v0, v0, v0 quad_perm:[1,0,3,2] row_mask:0xf bank_mask:0xf bound_ctrl:1
	s_nop 0
	v_addc_co_u32_e32 v57, vcc, 0, v57, vcc
	v_mov_b32_e32 v56, v160
	v_mov_b32_e32 v57, v161
	v_mov_b32_e32 v58, v162
	v_mov_b32_e32 v59, v163
	s_nop 0
	v_mov_b32_e32 v60, v164
	v_mov_b32_e32 v61, v165
	v_mov_b32_e32 v62, v166
	v_mov_b32_e32 v63, v167
	v_add_f32_dpp v0, v0, v0 quad_perm:[2,3,0,1] row_mask:0xf bank_mask:0xf bound_ctrl:1
	v_lshl_add_u64 v[48:49], v[48:49], 0, s[60:61]
	s_nop 0
	v_lshlrev_b32_e32 v64, 16, v56
	v_add_f32_dpp v0, v0, v0 row_half_mirror row_mask:0xf bank_mask:0xf bound_ctrl:1
	v_fmamk_f32 v0, v0, 0x3c000000, v194
	v_rsq_f32_e32 v6, v0
	v_mul_f32_e32 v0, 0xbfb8aa3b, v64
	v_exp_f32_e32 v0, v0
	v_mul_f32_e32 v65, v52, v6
	v_and_b32_e32 v52, 0xffff0000, v56
	v_add_f32_e32 v0, 1.0, v0
	v_rcp_f32_e32 v36, v0
	v_mul_f32_e32 v0, 0xbfb8aa3b, v52
	v_exp_f32_e32 v0, v0
	v_mul_f32_e32 v53, v53, v6
	v_mul_f32_e32 v21, v21, v6
	v_mul_f32_e32 v23, v23, v6
	v_add_f32_e32 v0, 1.0, v0
	v_rcp_f32_e32 v8, v0
	v_mul_f32_e32 v27, v27, v6
	v_mul_f32_e32 v19, v19, v6
	v_pk_mul_f32 v[64:65], v[36:37], v[64:65]
	v_pk_mul_f32 v[52:53], v[8:9], v[52:53]
	v_mul_f32_e32 v36, v64, v65
	v_mul_f32_e32 v8, v52, v53
	v_lshlrev_b32_e32 v52, 16, v57
	v_mul_f32_e32 v0, 0xbfb8aa3b, v52
	v_exp_f32_e32 v0, v0
	v_mul_f32_e32 v53, v54, v6
	v_add_f32_e32 v0, 1.0, v0
	v_rcp_f32_e32 v34, v0
	s_nop 0
	v_pk_mul_f32 v[52:53], v[34:35], v[52:53]
	s_nop 0
	v_mul_f32_e32 v34, v52, v53
	v_and_b32_e32 v52, 0xffff0000, v57
	v_mul_f32_e32 v0, 0xbfb8aa3b, v52
	v_exp_f32_e32 v0, v0
	v_mul_f32_e32 v53, v55, v6
	v_add_f32_e32 v0, 1.0, v0
	v_rcp_f32_e32 v10, v0
	s_nop 0
	v_pk_mul_f32 v[52:53], v[10:11], v[52:53]
	s_nop 0
	v_mul_f32_e32 v10, v52, v53
	v_lshlrev_b32_e32 v52, 16, v58
	v_mul_f32_e32 v0, 0xbfb8aa3b, v52
	v_exp_f32_e32 v0, v0
	v_mul_f32_e32 v53, v24, v6
	v_add_f32_e32 v0, 1.0, v0
	v_rcp_f32_e32 v32, v0
	s_nop 0
	v_pk_mul_f32 v[52:53], v[32:33], v[52:53]
	s_nop 0
	v_mul_f32_e32 v24, v52, v53
	v_and_b32_e32 v52, 0xffff0000, v58
	v_mul_f32_e32 v0, 0xbfb8aa3b, v52
	v_exp_f32_e32 v0, v0
	v_mul_f32_e32 v53, v25, v6
	v_add_f32_e32 v0, 1.0, v0
	v_rcp_f32_e32 v12, v0
	s_nop 0
	v_pk_mul_f32 v[52:53], v[12:13], v[52:53]
	s_nop 0
	v_mul_f32_e32 v12, v52, v53
	v_lshlrev_b32_e32 v52, 16, v59
	v_mul_f32_e32 v0, 0xbfb8aa3b, v52
	v_exp_f32_e32 v0, v0
	v_mul_f32_e32 v53, v26, v6
	v_and_b32_e32 v26, 0xffff0000, v59
	v_cvt_pk_bf16_f32 v24, v24, v12
	v_add_f32_e32 v0, 1.0, v0
	v_rcp_f32_e32 v30, v0
	v_mul_f32_e32 v0, 0xbfb8aa3b, v26
	v_exp_f32_e32 v0, v0
	v_pk_mul_f32 v[52:53], v[30:31], v[52:53]
	s_nop 0
	v_mul_f32_e32 v25, v52, v53
	v_add_f32_e32 v0, 1.0, v0
	s_nop 0
	v_lshlrev_b32_e32 v52, 16, v60
	v_rcp_f32_e32 v14, v0
	v_mul_f32_e32 v0, 0xbfb8aa3b, v52
	v_exp_f32_e32 v0, v0
	v_mul_f32_e32 v53, v20, v6
	v_and_b32_e32 v20, 0xffff0000, v60
	v_pk_mul_f32 v[26:27], v[14:15], v[26:27]
	v_add_f32_e32 v0, 1.0, v0
	v_rcp_f32_e32 v44, v0
	v_mul_f32_e32 v0, 0xbfb8aa3b, v20
	v_exp_f32_e32 v0, v0
	v_mul_f32_e32 v26, v26, v27
	v_cvt_pk_bf16_f32 v25, v25, v26
	v_pk_mul_f32 v[52:53], v[44:45], v[52:53]
	v_add_f32_e32 v0, 1.0, v0
	v_rcp_f32_e32 v0, v0
	v_mul_f32_e32 v14, v52, v53
	v_pk_mul_f32 v[20:21], v[0:1], v[20:21]
	s_nop 0
	v_mul_f32_e32 v0, v20, v21
	v_lshlrev_b32_e32 v20, 16, v61
	v_mul_f32_e32 v2, 0xbfb8aa3b, v20
	v_exp_f32_e32 v2, v2
	v_mul_f32_e32 v21, v22, v6
	v_and_b32_e32 v22, 0xffff0000, v61
	v_add_f32_e32 v2, 1.0, v2
	v_rcp_f32_e32 v42, v2
	v_mul_f32_e32 v2, 0xbfb8aa3b, v22
	v_exp_f32_e32 v2, v2
	v_pk_mul_f32 v[20:21], v[42:43], v[20:21]
	s_nop 0
	v_mul_f32_e32 v20, v20, v21
	v_add_f32_e32 v2, 1.0, v2
	v_rcp_f32_e32 v2, v2
	s_nop 0
	v_pk_mul_f32 v[22:23], v[2:3], v[22:23]
	s_nop 0
	v_mul_f32_e32 v2, v22, v23
	v_lshlrev_b32_e32 v22, 16, v62
	v_mul_f32_e32 v4, 0xbfb8aa3b, v22
	v_exp_f32_e32 v4, v4
	v_mul_f32_e32 v23, v16, v6
	v_add_f32_e32 v4, 1.0, v4
	v_rcp_f32_e32 v40, v4
	s_nop 0
	v_pk_mul_f32 v[22:23], v[40:41], v[22:23]
	s_nop 0
	v_mul_f32_e32 v16, v22, v23
	v_and_b32_e32 v22, 0xffff0000, v62
	v_mul_f32_e32 v4, 0xbfb8aa3b, v22
	v_exp_f32_e32 v4, v4
	v_mul_f32_e32 v23, v17, v6
	v_add_f32_e32 v4, 1.0, v4
	v_rcp_f32_e32 v4, v4
	s_nop 0
	v_pk_mul_f32 v[22:23], v[4:5], v[22:23]
	s_nop 0
	v_mul_f32_e32 v4, v22, v23
	v_mul_f32_e32 v23, v18, v6
	v_and_b32_e32 v18, 0xffff0000, v63
	v_mul_f32_e32 v6, 0xbfb8aa3b, v18
	v_exp_f32_e32 v6, v6
	v_lshlrev_b32_e32 v22, 16, v63
	v_mul_f32_e32 v17, 0xbfb8aa3b, v22
	v_exp_f32_e32 v17, v17
	v_add_f32_e32 v6, 1.0, v6
	v_rcp_f32_e32 v6, v6
	v_add_f32_e32 v17, 1.0, v17
	v_rcp_f32_e32 v38, v17
	v_pk_mul_f32 v[18:19], v[6:7], v[18:19]
	v_pk_mul_f32 v[22:23], v[38:39], v[22:23]
	v_mul_f32_e32 v6, v18, v19
	v_lshl_add_u64 v[18:19], v[28:29], 0, v[46:47]
	v_add_co_u32_e32 v26, vcc, s5, v18
	v_lshl_add_u64 v[46:47], v[46:47], 0, s[84:85]
	s_nop 0
	v_addc_co_u32_e32 v27, vcc, 0, v19, vcc
	v_mul_f32_e32 v17, v22, v23
	v_cvt_pk_bf16_f32 v22, v36, v8
	v_cvt_pk_bf16_f32 v23, v34, v10
	global_store_dwordx4 v[26:27], v[22:25], off offset:2048
	v_cvt_pk_bf16_f32 v18, v14, v0
	v_cvt_pk_bf16_f32 v19, v20, v2
	v_cvt_pk_bf16_f32 v20, v16, v4
	v_cvt_pk_bf16_f32 v21, v17, v6
	global_store_dwordx4 v[26:27], v[18:21], off offset:2064
	global_load_dwordx4 v[140:143], v[200:201], off nt
	global_load_dwordx4 v[144:147], v[200:201], off offset:16 nt
	global_load_dwordx4 v[148:151], v[200:201], off offset:32 nt
	global_load_dwordx4 v[156:159], v[200:201], off offset:48 nt
	global_load_dwordx4 v[160:163], v[202:203], off nt
	global_load_dwordx4 v[164:167], v[202:203], off offset:16 nt
	v_lshl_add_u64 v[200:201], v[200:201], 0, s[84:85]
	v_lshl_add_u64 v[202:203], v[202:203], 0, s[60:61]
	v_lshl_add_u64 v[16:17], v[28:29], 0, v[50:51]
	v_lshl_add_u64 v[18:19], v[16:17], 0, s[8:9]
	v_add_co_u32_e32 v16, vcc, 0x28e00000, v16
	s_mov_b64 s[6:7], 0x13c03800
	s_nop 0
	v_addc_co_u32_e32 v17, vcc, 0, v17, vcc
	s_waitcnt vmcnt(24)
; __device__ __forceinline__ float bflo(unsigned w) { return __uint_as_float(w << 16); }
; __device__ __forceinline__ float bfhi(unsigned w) { return __uint_as_float(w & 0xffff0000u); }
; __device__ __forceinline__ float rsq_f(float x) { return __builtin_amdgcn_rsqf(x); }
; __device__ __forceinline__ void onorm_pass(const float* obuf, const bf16_t* z, const float* ong, bf16_t* ycat, int gw, int NGW, int lane) {
;     ...
;     for (int row = gw; row < MP; row += NGW) {
;         const float* op = obuf + (size_t)row * 1024 + lane * 16; const bf16_t* zp = z + (size_t)row * NZ + 7168 + lane * 16;
;         f32x4 v[4]; float ss = 0.f;
; #pragma unroll
;         for (int i = 0; i < 4; ++i) { v[i] = *(const f32x4*)(op + 4 * i); ss += (v[i].x * v[i].x + v[i].y * v[i].y) + (v[i].z * v[i].z + v[i].w * v[i].w); }
;         const u32x4 g0 = *(const u32x4*)zp, g1 = *(const u32x4*)(zp + 8);
;         ss += __builtin_bit_cast(float, __builtin_amdgcn_update_dpp(0, __builtin_bit_cast(int, ss), 0xB1, 0xF, 0xF, true));
;         ss += __builtin_bit_cast(float, __builtin_amdgcn_update_dpp(0, __builtin_bit_cast(int, ss), 0x4E, 0xF, 0xF, true));
;         ss += __builtin_bit_cast(float, __builtin_amdgcn_update_dpp(0, __builtin_bit_cast(int, ss), 0x141, 0xF, 0xF, true));
;         const float rstd = rsq_f(ss * (1.f / HD) + EPS);
;         float y[16];
;         y[0] = v[0].x * rstd * g[0].x * silu_f(bflo(g0.x)); y[1] = v[0].y * rstd * g[0].y * silu_f(bfhi(g0.x)); y[2] = v[0].z * rstd * g[0].z * silu_f(bflo(g0.y)); y[3] = v[0].w * rstd * g[0].w * silu_f(bfhi(g0.y));
;         y[4] = v[1].x * rstd * g[1].x * silu_f(bflo(g0.z)); y[5] = v[1].y * rstd * g[1].y * silu_f(bfhi(g0.z)); y[6] = v[1].z * rstd * g[1].z * silu_f(bflo(g0.w)); y[7] = v[1].w * rstd * g[1].w * silu_f(bfhi(g0.w));
;         y[8] = v[2].x * rstd * g[2].x * silu_f(bflo(g1.x)); y[9] = v[2].y * rstd * g[2].y * silu_f(bfhi(g1.x)); y[10] = v[2].z * rstd * g[2].z * silu_f(bflo(g1.y)); y[11] = v[2].w * rstd * g[2].w * silu_f(bfhi(g1.y));
;         y[12] = v[3].x * rstd * g[3].x * silu_f(bflo(g1.z)); y[13] = v[3].y * rstd * g[3].y * silu_f(bfhi(g1.z)); y[14] = v[3].z * rstd * g[3].z * silu_f(bflo(g1.w)); y[15] = v[3].w * rstd * g[3].w * silu_f(bfhi(g1.w));
;         bf16_t* yp = ycat + (size_t)row * DM + 1024 + lane * 16;
;         *(u32x4*)yp = pack8(y); *(u32x4*)(yp + 8) = pack8(y + 8);
	v_mov_b32_e32 v52, v68
	v_mov_b32_e32 v53, v69
	v_mov_b32_e32 v54, v70
	v_mov_b32_e32 v55, v71
	v_mov_b32_e32 v20, v76
	v_mov_b32_e32 v21, v77
	v_mov_b32_e32 v22, v78
	v_mov_b32_e32 v23, v79
	v_mov_b32_e32 v24, v72
	v_mov_b32_e32 v25, v73
	v_mov_b32_e32 v26, v74
	v_mov_b32_e32 v27, v75
	s_nop 0
	v_mov_b32_e32 v16, v80
	v_mov_b32_e32 v17, v81
	v_mov_b32_e32 v18, v82
	v_mov_b32_e32 v19, v83
	s_mov_b32 s5, 0x20300000
	s_addk_i32 s4, 0x400
	v_lshl_add_u64 v[50:51], v[50:51], 0, s[84:85]
	s_cmpk_gt_i32 s4, 0x1bff
	s_nop 0
	v_pk_mul_f32 v[56:57], v[54:55], v[54:55]
	v_pk_mul_f32 v[58:59], v[52:53], v[52:53]
	s_nop 0
	v_mul_f32_e32 v0, v16, v16
	v_pk_mov_b32 v[60:61], v[58:59], v[56:57] op_sel:[1,0]
	v_mov_b32_e32 v59, v57
	v_pk_add_f32 v[56:57], v[60:61], v[58:59]
	v_pk_mul_f32 v[58:59], v[26:27], v[26:27]
	v_pk_mul_f32 v[60:61], v[24:25], v[24:25]
	v_mul_f32_e32 v2, v17, v17
	v_pk_mov_b32 v[62:63], v[60:61], v[58:59] op_sel:[1,0]
	v_mov_b32_e32 v61, v59
	v_pk_add_f32 v[58:59], v[62:63], v[60:61]
	v_pk_add_f32 v[56:57], v[56:57], v[56:57] op_sel:[0,1] op_sel_hi:[1,0]
	v_pk_add_f32 v[58:59], v[58:59], v[58:59] op_sel:[0,1] op_sel_hi:[1,0]
	v_mov_b32_e32 v57, v0
	v_mov_b32_e32 v59, v2
	v_mul_f32_e32 v0, v21, v21
	v_pk_add_f32 v[56:57], v[56:57], v[58:59]
	v_pk_fma_f32 v[58:59], v[20:21], v[20:21], v[0:1] op_sel_hi:[1,1,0]
	v_mul_f32_e32 v0, v23, v23
	v_mul_f32_e32 v4, v18, v18
	v_mul_f32_e32 v6, v19, v19
	v_pk_fma_f32 v[60:61], v[22:23], v[22:23], v[0:1] op_sel_hi:[1,1,0]
	v_mov_b32_e32 v59, v4
	v_mov_b32_e32 v61, v6
	v_pk_add_f32 v[58:59], v[58:59], v[60:61]
	s_nop 0
	v_pk_add_f32 v[56:57], v[56:57], v[58:59]
	s_nop 0
	v_add_f32_e32 v0, v56, v57
	v_lshl_add_u64 v[56:57], v[28:29], 0, v[48:49]
	v_lshl_add_u64 v[60:61], v[56:57], 0, s[6:7]
	v_add_co_u32_e32 v56, vcc, s76, v56
	v_add_f32_dpp v0, v0, v0 quad_perm:[1,0,3,2] row_mask:0xf bank_mask:0xf bound_ctrl:1
	s_nop 0
	v_addc_co_u32_e32 v57, vcc, 0, v57, vcc
	v_mov_b32_e32 v56, v84
	v_mov_b32_e32 v57, v85
	v_mov_b32_e32 v58, v86
	v_mov_b32_e32 v59, v87
	s_nop 0
	v_mov_b32_e32 v60, v88
	v_mov_b32_e32 v61, v89
	v_mov_b32_e32 v62, v90
	v_mov_b32_e32 v63, v91
	v_add_f32_dpp v0, v0, v0 quad_perm:[2,3,0,1] row_mask:0xf bank_mask:0xf bound_ctrl:1
	v_lshl_add_u64 v[48:49], v[48:49], 0, s[60:61]
	s_nop 0
	v_lshlrev_b32_e32 v64, 16, v56
	v_add_f32_dpp v0, v0, v0 row_half_mirror row_mask:0xf bank_mask:0xf bound_ctrl:1
	v_fmamk_f32 v0, v0, 0x3c000000, v194
	v_rsq_f32_e32 v6, v0
	v_mul_f32_e32 v0, 0xbfb8aa3b, v64
	v_exp_f32_e32 v0, v0
	v_mul_f32_e32 v65, v52, v6
	v_and_b32_e32 v52, 0xffff0000, v56
	v_add_f32_e32 v0, 1.0, v0
	v_rcp_f32_e32 v36, v0
	v_mul_f32_e32 v0, 0xbfb8aa3b, v52
	v_exp_f32_e32 v0, v0
	v_mul_f32_e32 v53, v53, v6
	v_mul_f32_e32 v21, v21, v6
	v_mul_f32_e32 v23, v23, v6
	v_add_f32_e32 v0, 1.0, v0
	v_rcp_f32_e32 v8, v0
	v_mul_f32_e32 v27, v27, v6
	v_mul_f32_e32 v19, v19, v6
	v_pk_mul_f32 v[64:65], v[36:37], v[64:65]
	v_pk_mul_f32 v[52:53], v[8:9], v[52:53]
	v_mul_f32_e32 v36, v64, v65
	v_mul_f32_e32 v8, v52, v53
	v_lshlrev_b32_e32 v52, 16, v57
	v_mul_f32_e32 v0, 0xbfb8aa3b, v52
	v_exp_f32_e32 v0, v0
	v_mul_f32_e32 v53, v54, v6
	v_add_f32_e32 v0, 1.0, v0
	v_rcp_f32_e32 v34, v0
	s_nop 0
	v_pk_mul_f32 v[52:53], v[34:35], v[52:53]
	s_nop 0
	v_mul_f32_e32 v34, v52, v53
	v_and_b32_e32 v52, 0xffff0000, v57
	v_mul_f32_e32 v0, 0xbfb8aa3b, v52
	v_exp_f32_e32 v0, v0
	v_mul_f32_e32 v53, v55, v6
	v_add_f32_e32 v0, 1.0, v0
	v_rcp_f32_e32 v10, v0
	s_nop 0
	v_pk_mul_f32 v[52:53], v[10:11], v[52:53]
	s_nop 0
	v_mul_f32_e32 v10, v52, v53
	v_lshlrev_b32_e32 v52, 16, v58
	v_mul_f32_e32 v0, 0xbfb8aa3b, v52
	v_exp_f32_e32 v0, v0
	v_mul_f32_e32 v53, v24, v6
	v_add_f32_e32 v0, 1.0, v0
	v_rcp_f32_e32 v32, v0
	s_nop 0
	v_pk_mul_f32 v[52:53], v[32:33], v[52:53]
	s_nop 0
	v_mul_f32_e32 v24, v52, v53
	v_and_b32_e32 v52, 0xffff0000, v58
	v_mul_f32_e32 v0, 0xbfb8aa3b, v52
	v_exp_f32_e32 v0, v0
	v_mul_f32_e32 v53, v25, v6
	v_add_f32_e32 v0, 1.0, v0
	v_rcp_f32_e32 v12, v0
	s_nop 0
	v_pk_mul_f32 v[52:53], v[12:13], v[52:53]
	s_nop 0
	v_mul_f32_e32 v12, v52, v53
	v_lshlrev_b32_e32 v52, 16, v59
	v_mul_f32_e32 v0, 0xbfb8aa3b, v52
	v_exp_f32_e32 v0, v0
	v_mul_f32_e32 v53, v26, v6
	v_and_b32_e32 v26, 0xffff0000, v59
	v_cvt_pk_bf16_f32 v24, v24, v12
	v_add_f32_e32 v0, 1.0, v0
	v_rcp_f32_e32 v30, v0
	v_mul_f32_e32 v0, 0xbfb8aa3b, v26
	v_exp_f32_e32 v0, v0
	v_pk_mul_f32 v[52:53], v[30:31], v[52:53]
	s_nop 0
	v_mul_f32_e32 v25, v52, v53
	v_add_f32_e32 v0, 1.0, v0
	s_nop 0
	v_lshlrev_b32_e32 v52, 16, v60
	v_rcp_f32_e32 v14, v0
	v_mul_f32_e32 v0, 0xbfb8aa3b, v52
	v_exp_f32_e32 v0, v0
	v_mul_f32_e32 v53, v20, v6
	v_and_b32_e32 v20, 0xffff0000, v60
	v_pk_mul_f32 v[26:27], v[14:15], v[26:27]
	v_add_f32_e32 v0, 1.0, v0
	v_rcp_f32_e32 v44, v0
	v_mul_f32_e32 v0, 0xbfb8aa3b, v20
	v_exp_f32_e32 v0, v0
	v_mul_f32_e32 v26, v26, v27
	v_cvt_pk_bf16_f32 v25, v25, v26
	v_pk_mul_f32 v[52:53], v[44:45], v[52:53]
	v_add_f32_e32 v0, 1.0, v0
	v_rcp_f32_e32 v0, v0
	v_mul_f32_e32 v14, v52, v53
	v_pk_mul_f32 v[20:21], v[0:1], v[20:21]
	s_nop 0
	v_mul_f32_e32 v0, v20, v21
	v_lshlrev_b32_e32 v20, 16, v61
	v_mul_f32_e32 v2, 0xbfb8aa3b, v20
	v_exp_f32_e32 v2, v2
	v_mul_f32_e32 v21, v22, v6
	v_and_b32_e32 v22, 0xffff0000, v61
	v_add_f32_e32 v2, 1.0, v2
	v_rcp_f32_e32 v42, v2
	v_mul_f32_e32 v2, 0xbfb8aa3b, v22
	v_exp_f32_e32 v2, v2
	v_pk_mul_f32 v[20:21], v[42:43], v[20:21]
	s_nop 0
	v_mul_f32_e32 v20, v20, v21
	v_add_f32_e32 v2, 1.0, v2
	v_rcp_f32_e32 v2, v2
	s_nop 0
	v_pk_mul_f32 v[22:23], v[2:3], v[22:23]
	s_nop 0
	v_mul_f32_e32 v2, v22, v23
	v_lshlrev_b32_e32 v22, 16, v62
	v_mul_f32_e32 v4, 0xbfb8aa3b, v22
	v_exp_f32_e32 v4, v4
	v_mul_f32_e32 v23, v16, v6
; __device__ __forceinline__ float bflo(unsigned w) { return __uint_as_float(w << 16); }
; __device__ __forceinline__ float bfhi(unsigned w) { return __uint_as_float(w & 0xffff0000u); }
; __device__ __forceinline__ float rsq_f(float x) { return __builtin_amdgcn_rsqf(x); }
; __device__ __forceinline__ void onorm_pass(const float* obuf, const bf16_t* z, const float* ong, bf16_t* ycat, int gw, int NGW, int lane) {
;     ...
;     for (int row = gw; row < MP; row += NGW) {
;         const float* op = obuf + (size_t)row * 1024 + lane * 16; const bf16_t* zp = z + (size_t)row * NZ + 7168 + lane * 16;
;         f32x4 v[4]; float ss = 0.f;
; #pragma unroll
;         for (int i = 0; i < 4; ++i) { v[i] = *(const f32x4*)(op + 4 * i); ss += (v[i].x * v[i].x + v[i].y * v[i].y) + (v[i].z * v[i].z + v[i].w * v[i].w); }
;         const u32x4 g0 = *(const u32x4*)zp, g1 = *(const u32x4*)(zp + 8);
;         ss += __builtin_bit_cast(float, __builtin_amdgcn_update_dpp(0, __builtin_bit_cast(int, ss), 0xB1, 0xF, 0xF, true));
;         ss += __builtin_bit_cast(float, __builtin_amdgcn_update_dpp(0, __builtin_bit_cast(int, ss), 0x4E, 0xF, 0xF, true));
;         ss += __builtin_bit_cast(float, __builtin_amdgcn_update_dpp(0, __builtin_bit_cast(int, ss), 0x141, 0xF, 0xF, true));
;         const float rstd = rsq_f(ss * (1.f / HD) + EPS);
;         float y[16];
;         y[0] = v[0].x * rstd * g[0].x * silu_f(bflo(g0.x)); y[1] = v[0].y * rstd * g[0].y * silu_f(bfhi(g0.x)); y[2] = v[0].z * rstd * g[0].z * silu_f(bflo(g0.y)); y[3] = v[0].w * rstd * g[0].w * silu_f(bfhi(g0.y));
;         y[4] = v[1].x * rstd * g[1].x * silu_f(bflo(g0.z)); y[5] = v[1].y * rstd * g[1].y * silu_f(bfhi(g0.z)); y[6] = v[1].z * rstd * g[1].z * silu_f(bflo(g0.w)); y[7] = v[1].w * rstd * g[1].w * silu_f(bfhi(g0.w));
;         y[8] = v[2].x * rstd * g[2].x * silu_f(bflo(g1.x)); y[9] = v[2].y * rstd * g[2].y * silu_f(bfhi(g1.x)); y[10] = v[2].z * rstd * g[2].z * silu_f(bflo(g1.y)); y[11] = v[2].w * rstd * g[2].w * silu_f(bfhi(g1.y));
;         y[12] = v[3].x * rstd * g[3].x * silu_f(bflo(g1.z)); y[13] = v[3].y * rstd * g[3].y * silu_f(bfhi(g1.z)); y[14] = v[3].z * rstd * g[3].z * silu_f(bflo(g1.w)); y[15] = v[3].w * rstd * g[3].w * silu_f(bfhi(g1.w));
;         bf16_t* yp = ycat + (size_t)row * DM + 1024 + lane * 16;
;         *(u32x4*)yp = pack8(y); *(u32x4*)(yp + 8) = pack8(y + 8);
	v_add_f32_e32 v4, 1.0, v4
	v_rcp_f32_e32 v40, v4
	s_nop 0
	v_pk_mul_f32 v[22:23], v[40:41], v[22:23]
	s_nop 0
	v_mul_f32_e32 v16, v22, v23
	v_and_b32_e32 v22, 0xffff0000, v62
	v_mul_f32_e32 v4, 0xbfb8aa3b, v22
	v_exp_f32_e32 v4, v4
	v_mul_f32_e32 v23, v17, v6
	v_add_f32_e32 v4, 1.0, v4
	v_rcp_f32_e32 v4, v4
	s_nop 0
	v_pk_mul_f32 v[22:23], v[4:5], v[22:23]
	s_nop 0
	v_mul_f32_e32 v4, v22, v23
	v_mul_f32_e32 v23, v18, v6
	v_and_b32_e32 v18, 0xffff0000, v63
	v_mul_f32_e32 v6, 0xbfb8aa3b, v18
	v_exp_f32_e32 v6, v6
	v_lshlrev_b32_e32 v22, 16, v63
	v_mul_f32_e32 v17, 0xbfb8aa3b, v22
	v_exp_f32_e32 v17, v17
	v_add_f32_e32 v6, 1.0, v6
	v_rcp_f32_e32 v6, v6
	v_add_f32_e32 v17, 1.0, v17
	v_rcp_f32_e32 v38, v17
	v_pk_mul_f32 v[18:19], v[6:7], v[18:19]
	v_pk_mul_f32 v[22:23], v[38:39], v[22:23]
	v_mul_f32_e32 v6, v18, v19
	v_lshl_add_u64 v[18:19], v[28:29], 0, v[46:47]
	v_add_co_u32_e32 v26, vcc, s5, v18
	v_lshl_add_u64 v[46:47], v[46:47], 0, s[84:85]
	s_nop 0
	v_addc_co_u32_e32 v27, vcc, 0, v19, vcc
	v_mul_f32_e32 v17, v22, v23
	v_cvt_pk_bf16_f32 v22, v36, v8
	v_cvt_pk_bf16_f32 v23, v34, v10
	global_store_dwordx4 v[26:27], v[22:25], off offset:2048
	v_cvt_pk_bf16_f32 v18, v14, v0
	v_cvt_pk_bf16_f32 v19, v20, v2
	v_cvt_pk_bf16_f32 v20, v16, v4
	v_cvt_pk_bf16_f32 v21, v17, v6
	global_store_dwordx4 v[26:27], v[18:21], off offset:2064
	v_lshl_add_u64 v[16:17], v[28:29], 0, v[50:51]
	v_lshl_add_u64 v[18:19], v[16:17], 0, s[8:9]
	v_add_co_u32_e32 v16, vcc, 0x28e00000, v16
	s_mov_b64 s[6:7], 0x13c03800
	s_nop 0
	v_addc_co_u32_e32 v17, vcc, 0, v17, vcc
	s_waitcnt vmcnt(18)
	v_mov_b32_e32 v52, v92
	v_mov_b32_e32 v53, v93
	v_mov_b32_e32 v54, v94
	v_mov_b32_e32 v55, v95
	v_mov_b32_e32 v20, v100
	v_mov_b32_e32 v21, v101
	v_mov_b32_e32 v22, v102
	v_mov_b32_e32 v23, v103
	v_mov_b32_e32 v24, v96
	v_mov_b32_e32 v25, v97
	v_mov_b32_e32 v26, v98
	v_mov_b32_e32 v27, v99
	s_nop 0
	v_mov_b32_e32 v16, v104
	v_mov_b32_e32 v17, v105
	v_mov_b32_e32 v18, v106
	v_mov_b32_e32 v19, v107
	s_mov_b32 s5, 0x20300000
	s_addk_i32 s4, 0x400
	v_lshl_add_u64 v[50:51], v[50:51], 0, s[84:85]
	s_cmpk_gt_i32 s4, 0x1bff
	s_nop 0
	v_pk_mul_f32 v[56:57], v[54:55], v[54:55]
	v_pk_mul_f32 v[58:59], v[52:53], v[52:53]
	s_nop 0
	v_mul_f32_e32 v0, v16, v16
	v_pk_mov_b32 v[60:61], v[58:59], v[56:57] op_sel:[1,0]
	v_mov_b32_e32 v59, v57
	v_pk_add_f32 v[56:57], v[60:61], v[58:59]
	v_pk_mul_f32 v[58:59], v[26:27], v[26:27]
	v_pk_mul_f32 v[60:61], v[24:25], v[24:25]
	v_mul_f32_e32 v2, v17, v17
	v_pk_mov_b32 v[62:63], v[60:61], v[58:59] op_sel:[1,0]
	v_mov_b32_e32 v61, v59
	v_pk_add_f32 v[58:59], v[62:63], v[60:61]
	v_pk_add_f32 v[56:57], v[56:57], v[56:57] op_sel:[0,1] op_sel_hi:[1,0]
	v_pk_add_f32 v[58:59], v[58:59], v[58:59] op_sel:[0,1] op_sel_hi:[1,0]
	v_mov_b32_e32 v57, v0
	v_mov_b32_e32 v59, v2
	v_mul_f32_e32 v0, v21, v21
	v_pk_add_f32 v[56:57], v[56:57], v[58:59]
	v_pk_fma_f32 v[58:59], v[20:21], v[20:21], v[0:1] op_sel_hi:[1,1,0]
	v_mul_f32_e32 v0, v23, v23
	v_mul_f32_e32 v4, v18, v18
	v_mul_f32_e32 v6, v19, v19
	v_pk_fma_f32 v[60:61], v[22:23], v[22:23], v[0:1] op_sel_hi:[1,1,0]
	v_mov_b32_e32 v59, v4
	v_mov_b32_e32 v61, v6
	v_pk_add_f32 v[58:59], v[58:59], v[60:61]
	s_nop 0
	v_pk_add_f32 v[56:57], v[56:57], v[58:59]
	s_nop 0
	v_add_f32_e32 v0, v56, v57
	v_lshl_add_u64 v[56:57], v[28:29], 0, v[48:49]
	v_lshl_add_u64 v[60:61], v[56:57], 0, s[6:7]
	v_add_co_u32_e32 v56, vcc, s76, v56
	v_add_f32_dpp v0, v0, v0 quad_perm:[1,0,3,2] row_mask:0xf bank_mask:0xf bound_ctrl:1
	s_nop 0
	v_addc_co_u32_e32 v57, vcc, 0, v57, vcc
	v_mov_b32_e32 v56, v108
	v_mov_b32_e32 v57, v109
	v_mov_b32_e32 v58, v110
	v_mov_b32_e32 v59, v111
	s_nop 0
	v_mov_b32_e32 v60, v112
	v_mov_b32_e32 v61, v113
	v_mov_b32_e32 v62, v114
	v_mov_b32_e32 v63, v115
	v_add_f32_dpp v0, v0, v0 quad_perm:[2,3,0,1] row_mask:0xf bank_mask:0xf bound_ctrl:1
	v_lshl_add_u64 v[48:49], v[48:49], 0, s[60:61]
	s_nop 0
	v_lshlrev_b32_e32 v64, 16, v56
	v_add_f32_dpp v0, v0, v0 row_half_mirror row_mask:0xf bank_mask:0xf bound_ctrl:1
	v_fmamk_f32 v0, v0, 0x3c000000, v194
	v_rsq_f32_e32 v6, v0
	v_mul_f32_e32 v0, 0xbfb8aa3b, v64
	v_exp_f32_e32 v0, v0
	v_mul_f32_e32 v65, v52, v6
	v_and_b32_e32 v52, 0xffff0000, v56
	v_add_f32_e32 v0, 1.0, v0
	v_rcp_f32_e32 v36, v0
	v_mul_f32_e32 v0, 0xbfb8aa3b, v52
	v_exp_f32_e32 v0, v0
	v_mul_f32_e32 v53, v53, v6
	v_mul_f32_e32 v21, v21, v6
	v_mul_f32_e32 v23, v23, v6
	v_add_f32_e32 v0, 1.0, v0
	v_rcp_f32_e32 v8, v0
	v_mul_f32_e32 v27, v27, v6
	v_mul_f32_e32 v19, v19, v6
	v_pk_mul_f32 v[64:65], v[36:37], v[64:65]
	v_pk_mul_f32 v[52:53], v[8:9], v[52:53]
	v_mul_f32_e32 v36, v64, v65
	v_mul_f32_e32 v8, v52, v53
	v_lshlrev_b32_e32 v52, 16, v57
	v_mul_f32_e32 v0, 0xbfb8aa3b, v52
	v_exp_f32_e32 v0, v0
	v_mul_f32_e32 v53, v54, v6
	v_add_f32_e32 v0, 1.0, v0
	v_rcp_f32_e32 v34, v0
	s_nop 0
	v_pk_mul_f32 v[52:53], v[34:35], v[52:53]
	s_nop 0
	v_mul_f32_e32 v34, v52, v53
	v_and_b32_e32 v52, 0xffff0000, v57
	v_mul_f32_e32 v0, 0xbfb8aa3b, v52
	v_exp_f32_e32 v0, v0
	v_mul_f32_e32 v53, v55, v6
	v_add_f32_e32 v0, 1.0, v0
	v_rcp_f32_e32 v10, v0
	s_nop 0
	v_pk_mul_f32 v[52:53], v[10:11], v[52:53]
	s_nop 0
	v_mul_f32_e32 v10, v52, v53
	v_lshlrev_b32_e32 v52, 16, v58
	v_mul_f32_e32 v0, 0xbfb8aa3b, v52
	v_exp_f32_e32 v0, v0
	v_mul_f32_e32 v53, v24, v6
	v_add_f32_e32 v0, 1.0, v0
	v_rcp_f32_e32 v32, v0
	s_nop 0
	v_pk_mul_f32 v[52:53], v[32:33], v[52:53]
	s_nop 0
	v_mul_f32_e32 v24, v52, v53
	v_and_b32_e32 v52, 0xffff0000, v58
	v_mul_f32_e32 v0, 0xbfb8aa3b, v52
	v_exp_f32_e32 v0, v0
	v_mul_f32_e32 v53, v25, v6
	v_add_f32_e32 v0, 1.0, v0
	v_rcp_f32_e32 v12, v0
	s_nop 0
	v_pk_mul_f32 v[52:53], v[12:13], v[52:53]
	s_nop 0
	v_mul_f32_e32 v12, v52, v53
; __device__ __forceinline__ float bflo(unsigned w) { return __uint_as_float(w << 16); }
; __device__ __forceinline__ float bfhi(unsigned w) { return __uint_as_float(w & 0xffff0000u); }
; __device__ __forceinline__ float rsq_f(float x) { return __builtin_amdgcn_rsqf(x); }
; __device__ __forceinline__ void onorm_pass(const float* obuf, const bf16_t* z, const float* ong, bf16_t* ycat, int gw, int NGW, int lane) {
;     ...
;     for (int row = gw; row < MP; row += NGW) {
;         const float* op = obuf + (size_t)row * 1024 + lane * 16; const bf16_t* zp = z + (size_t)row * NZ + 7168 + lane * 16;
;         f32x4 v[4]; float ss = 0.f;
; #pragma unroll
;         for (int i = 0; i < 4; ++i) { v[i] = *(const f32x4*)(op + 4 * i); ss += (v[i].x * v[i].x + v[i].y * v[i].y) + (v[i].z * v[i].z + v[i].w * v[i].w); }
;         const u32x4 g0 = *(const u32x4*)zp, g1 = *(const u32x4*)(zp + 8);
;         ss += __builtin_bit_cast(float, __builtin_amdgcn_update_dpp(0, __builtin_bit_cast(int, ss), 0xB1, 0xF, 0xF, true));
;         ss += __builtin_bit_cast(float, __builtin_amdgcn_update_dpp(0, __builtin_bit_cast(int, ss), 0x4E, 0xF, 0xF, true));
;         ss += __builtin_bit_cast(float, __builtin_amdgcn_update_dpp(0, __builtin_bit_cast(int, ss), 0x141, 0xF, 0xF, true));
;         const float rstd = rsq_f(ss * (1.f / HD) + EPS);
;         float y[16];
;         y[0] = v[0].x * rstd * g[0].x * silu_f(bflo(g0.x)); y[1] = v[0].y * rstd * g[0].y * silu_f(bfhi(g0.x)); y[2] = v[0].z * rstd * g[0].z * silu_f(bflo(g0.y)); y[3] = v[0].w * rstd * g[0].w * silu_f(bfhi(g0.y));
;         y[4] = v[1].x * rstd * g[1].x * silu_f(bflo(g0.z)); y[5] = v[1].y * rstd * g[1].y * silu_f(bfhi(g0.z)); y[6] = v[1].z * rstd * g[1].z * silu_f(bflo(g0.w)); y[7] = v[1].w * rstd * g[1].w * silu_f(bfhi(g0.w));
;         y[8] = v[2].x * rstd * g[2].x * silu_f(bflo(g1.x)); y[9] = v[2].y * rstd * g[2].y * silu_f(bfhi(g1.x)); y[10] = v[2].z * rstd * g[2].z * silu_f(bflo(g1.y)); y[11] = v[2].w * rstd * g[2].w * silu_f(bfhi(g1.y));
;         y[12] = v[3].x * rstd * g[3].x * silu_f(bflo(g1.z)); y[13] = v[3].y * rstd * g[3].y * silu_f(bfhi(g1.z)); y[14] = v[3].z * rstd * g[3].z * silu_f(bflo(g1.w)); y[15] = v[3].w * rstd * g[3].w * silu_f(bfhi(g1.w));
;         bf16_t* yp = ycat + (size_t)row * DM + 1024 + lane * 16;
;         *(u32x4*)yp = pack8(y); *(u32x4*)(yp + 8) = pack8(y + 8);
	v_lshlrev_b32_e32 v52, 16, v59
	v_mul_f32_e32 v0, 0xbfb8aa3b, v52
	v_exp_f32_e32 v0, v0
	v_mul_f32_e32 v53, v26, v6
	v_and_b32_e32 v26, 0xffff0000, v59
	v_cvt_pk_bf16_f32 v24, v24, v12
	v_add_f32_e32 v0, 1.0, v0
	v_rcp_f32_e32 v30, v0
	v_mul_f32_e32 v0, 0xbfb8aa3b, v26
	v_exp_f32_e32 v0, v0
	v_pk_mul_f32 v[52:53], v[30:31], v[52:53]
	s_nop 0
	v_mul_f32_e32 v25, v52, v53
	v_add_f32_e32 v0, 1.0, v0
	s_nop 0
	v_lshlrev_b32_e32 v52, 16, v60
	v_rcp_f32_e32 v14, v0
	v_mul_f32_e32 v0, 0xbfb8aa3b, v52
	v_exp_f32_e32 v0, v0
	v_mul_f32_e32 v53, v20, v6
	v_and_b32_e32 v20, 0xffff0000, v60
	v_pk_mul_f32 v[26:27], v[14:15], v[26:27]
	v_add_f32_e32 v0, 1.0, v0
	v_rcp_f32_e32 v44, v0
	v_mul_f32_e32 v0, 0xbfb8aa3b, v20
	v_exp_f32_e32 v0, v0
	v_mul_f32_e32 v26, v26, v27
	v_cvt_pk_bf16_f32 v25, v25, v26
	v_pk_mul_f32 v[52:53], v[44:45], v[52:53]
	v_add_f32_e32 v0, 1.0, v0
	v_rcp_f32_e32 v0, v0
	v_mul_f32_e32 v14, v52, v53
	v_pk_mul_f32 v[20:21], v[0:1], v[20:21]
	s_nop 0
	v_mul_f32_e32 v0, v20, v21
	v_lshlrev_b32_e32 v20, 16, v61
	v_mul_f32_e32 v2, 0xbfb8aa3b, v20
	v_exp_f32_e32 v2, v2
	v_mul_f32_e32 v21, v22, v6
	v_and_b32_e32 v22, 0xffff0000, v61
	v_add_f32_e32 v2, 1.0, v2
	v_rcp_f32_e32 v42, v2
	v_mul_f32_e32 v2, 0xbfb8aa3b, v22
	v_exp_f32_e32 v2, v2
	v_pk_mul_f32 v[20:21], v[42:43], v[20:21]
	s_nop 0
	v_mul_f32_e32 v20, v20, v21
	v_add_f32_e32 v2, 1.0, v2
	v_rcp_f32_e32 v2, v2
	s_nop 0
	v_pk_mul_f32 v[22:23], v[2:3], v[22:23]
	s_nop 0
	v_mul_f32_e32 v2, v22, v23
	v_lshlrev_b32_e32 v22, 16, v62
	v_mul_f32_e32 v4, 0xbfb8aa3b, v22
	v_exp_f32_e32 v4, v4
	v_mul_f32_e32 v23, v16, v6
	v_add_f32_e32 v4, 1.0, v4
	v_rcp_f32_e32 v40, v4
	s_nop 0
	v_pk_mul_f32 v[22:23], v[40:41], v[22:23]
	s_nop 0
	v_mul_f32_e32 v16, v22, v23
	v_and_b32_e32 v22, 0xffff0000, v62
	v_mul_f32_e32 v4, 0xbfb8aa3b, v22
	v_exp_f32_e32 v4, v4
	v_mul_f32_e32 v23, v17, v6
	v_add_f32_e32 v4, 1.0, v4
	v_rcp_f32_e32 v4, v4
	s_nop 0
	v_pk_mul_f32 v[22:23], v[4:5], v[22:23]
	s_nop 0
	v_mul_f32_e32 v4, v22, v23
	v_mul_f32_e32 v23, v18, v6
	v_and_b32_e32 v18, 0xffff0000, v63
	v_mul_f32_e32 v6, 0xbfb8aa3b, v18
	v_exp_f32_e32 v6, v6
	v_lshlrev_b32_e32 v22, 16, v63
	v_mul_f32_e32 v17, 0xbfb8aa3b, v22
	v_exp_f32_e32 v17, v17
	v_add_f32_e32 v6, 1.0, v6
	v_rcp_f32_e32 v6, v6
	v_add_f32_e32 v17, 1.0, v17
	v_rcp_f32_e32 v38, v17
	v_pk_mul_f32 v[18:19], v[6:7], v[18:19]
	v_pk_mul_f32 v[22:23], v[38:39], v[22:23]
	v_mul_f32_e32 v6, v18, v19
	v_lshl_add_u64 v[18:19], v[28:29], 0, v[46:47]
	v_add_co_u32_e32 v26, vcc, s5, v18
	v_lshl_add_u64 v[46:47], v[46:47], 0, s[84:85]
	s_nop 0
	v_addc_co_u32_e32 v27, vcc, 0, v19, vcc
	v_mul_f32_e32 v17, v22, v23
	v_cvt_pk_bf16_f32 v22, v36, v8
	v_cvt_pk_bf16_f32 v23, v34, v10
	global_store_dwordx4 v[26:27], v[22:25], off offset:2048
	v_cvt_pk_bf16_f32 v18, v14, v0
	v_cvt_pk_bf16_f32 v19, v20, v2
	v_cvt_pk_bf16_f32 v20, v16, v4
	v_cvt_pk_bf16_f32 v21, v17, v6
	global_store_dwordx4 v[26:27], v[18:21], off offset:2064
	v_lshl_add_u64 v[16:17], v[28:29], 0, v[50:51]
	v_lshl_add_u64 v[18:19], v[16:17], 0, s[8:9]
	v_add_co_u32_e32 v16, vcc, 0x28e00000, v16
	s_mov_b64 s[6:7], 0x13c03800
	s_nop 0
	v_addc_co_u32_e32 v17, vcc, 0, v17, vcc
	s_waitcnt vmcnt(12)
	v_mov_b32_e32 v52, v116
	v_mov_b32_e32 v53, v117
	v_mov_b32_e32 v54, v118
	v_mov_b32_e32 v55, v119
	v_mov_b32_e32 v20, v124
	v_mov_b32_e32 v21, v125
	v_mov_b32_e32 v22, v126
	v_mov_b32_e32 v23, v127
	v_mov_b32_e32 v24, v120
	v_mov_b32_e32 v25, v121
	v_mov_b32_e32 v26, v122
	v_mov_b32_e32 v27, v123
	s_nop 0
	v_mov_b32_e32 v16, v128
	v_mov_b32_e32 v17, v129
	v_mov_b32_e32 v18, v130
	v_mov_b32_e32 v19, v131
	s_mov_b32 s5, 0x20300000
	s_addk_i32 s4, 0x400
	v_lshl_add_u64 v[50:51], v[50:51], 0, s[84:85]
	s_cmpk_gt_i32 s4, 0x1bff
	s_nop 0
	v_pk_mul_f32 v[56:57], v[54:55], v[54:55]
	v_pk_mul_f32 v[58:59], v[52:53], v[52:53]
	s_nop 0
	v_mul_f32_e32 v0, v16, v16
	v_pk_mov_b32 v[60:61], v[58:59], v[56:57] op_sel:[1,0]
	v_mov_b32_e32 v59, v57
	v_pk_add_f32 v[56:57], v[60:61], v[58:59]
	v_pk_mul_f32 v[58:59], v[26:27], v[26:27]
	v_pk_mul_f32 v[60:61], v[24:25], v[24:25]
	v_mul_f32_e32 v2, v17, v17
	v_pk_mov_b32 v[62:63], v[60:61], v[58:59] op_sel:[1,0]
	v_mov_b32_e32 v61, v59
	v_pk_add_f32 v[58:59], v[62:63], v[60:61]
	v_pk_add_f32 v[56:57], v[56:57], v[56:57] op_sel:[0,1] op_sel_hi:[1,0]
	v_pk_add_f32 v[58:59], v[58:59], v[58:59] op_sel:[0,1] op_sel_hi:[1,0]
	v_mov_b32_e32 v57, v0
	v_mov_b32_e32 v59, v2
	v_mul_f32_e32 v0, v21, v21
	v_pk_add_f32 v[56:57], v[56:57], v[58:59]
	v_pk_fma_f32 v[58:59], v[20:21], v[20:21], v[0:1] op_sel_hi:[1,1,0]
	v_mul_f32_e32 v0, v23, v23
	v_mul_f32_e32 v4, v18, v18
	v_mul_f32_e32 v6, v19, v19
	v_pk_fma_f32 v[60:61], v[22:23], v[22:23], v[0:1] op_sel_hi:[1,1,0]
	v_mov_b32_e32 v59, v4
	v_mov_b32_e32 v61, v6
	v_pk_add_f32 v[58:59], v[58:59], v[60:61]
	s_nop 0
	v_pk_add_f32 v[56:57], v[56:57], v[58:59]
	s_nop 0
	v_add_f32_e32 v0, v56, v57
	v_lshl_add_u64 v[56:57], v[28:29], 0, v[48:49]
	v_lshl_add_u64 v[60:61], v[56:57], 0, s[6:7]
	v_add_co_u32_e32 v56, vcc, s76, v56
	v_add_f32_dpp v0, v0, v0 quad_perm:[1,0,3,2] row_mask:0xf bank_mask:0xf bound_ctrl:1
	s_nop 0
	v_addc_co_u32_e32 v57, vcc, 0, v57, vcc
	v_mov_b32_e32 v56, v132
	v_mov_b32_e32 v57, v133
	v_mov_b32_e32 v58, v134
	v_mov_b32_e32 v59, v135
	s_nop 0
	v_mov_b32_e32 v60, v136
	v_mov_b32_e32 v61, v137
	v_mov_b32_e32 v62, v138
	v_mov_b32_e32 v63, v139
	v_add_f32_dpp v0, v0, v0 quad_perm:[2,3,0,1] row_mask:0xf bank_mask:0xf bound_ctrl:1
	v_lshl_add_u64 v[48:49], v[48:49], 0, s[60:61]
	s_nop 0
	v_lshlrev_b32_e32 v64, 16, v56
	v_add_f32_dpp v0, v0, v0 row_half_mirror row_mask:0xf bank_mask:0xf bound_ctrl:1
	v_fmamk_f32 v0, v0, 0x3c000000, v194
; __device__ __forceinline__ float bflo(unsigned w) { return __uint_as_float(w << 16); }
; __device__ __forceinline__ float bfhi(unsigned w) { return __uint_as_float(w & 0xffff0000u); }
; __device__ __forceinline__ float rsq_f(float x) { return __builtin_amdgcn_rsqf(x); }
; __device__ __forceinline__ float silu_f(float x) { return x * rcp_f(1.f + exp_f(-x)); }
; __device__ __forceinline__ u32x4 pack8(const float* v) { u32x4 o; o.x = pk2(v[0], v[1]); o.y = pk2(v[2], v[3]); o.z = pk2(v[4], v[5]); o.w = pk2(v[6], v[7]); return o; }
; __device__ __forceinline__ void onorm_pass(const float* obuf, const bf16_t* z, const float* ong, bf16_t* ycat, int gw, int NGW, int lane) {
;     ...
;         const float rstd = rsq_f(ss * (1.f / HD) + EPS);
;         float y[16];
;         y[0] = v[0].x * rstd * g[0].x * silu_f(bflo(g0.x)); y[1] = v[0].y * rstd * g[0].y * silu_f(bfhi(g0.x)); y[2] = v[0].z * rstd * g[0].z * silu_f(bflo(g0.y)); y[3] = v[0].w * rstd * g[0].w * silu_f(bfhi(g0.y));
;         y[4] = v[1].x * rstd * g[1].x * silu_f(bflo(g0.z)); y[5] = v[1].y * rstd * g[1].y * silu_f(bfhi(g0.z)); y[6] = v[1].z * rstd * g[1].z * silu_f(bflo(g0.w)); y[7] = v[1].w * rstd * g[1].w * silu_f(bfhi(g0.w));
;         y[8] = v[2].x * rstd * g[2].x * silu_f(bflo(g1.x)); y[9] = v[2].y * rstd * g[2].y * silu_f(bfhi(g1.x)); y[10] = v[2].z * rstd * g[2].z * silu_f(bflo(g1.y)); y[11] = v[2].w * rstd * g[2].w * silu_f(bfhi(g1.y));
;         y[12] = v[3].x * rstd * g[3].x * silu_f(bflo(g1.z)); y[13] = v[3].y * rstd * g[3].y * silu_f(bfhi(g1.z)); y[14] = v[3].z * rstd * g[3].z * silu_f(bflo(g1.w)); y[15] = v[3].w * rstd * g[3].w * silu_f(bfhi(g1.w));
;         bf16_t* yp = ycat + (size_t)row * DM + 1024 + lane * 16;
;         *(u32x4*)yp = pack8(y); *(u32x4*)(yp + 8) = pack8(y + 8);
	v_rsq_f32_e32 v6, v0
	v_mul_f32_e32 v0, 0xbfb8aa3b, v64
	v_exp_f32_e32 v0, v0
	v_mul_f32_e32 v65, v52, v6
	v_and_b32_e32 v52, 0xffff0000, v56
	v_add_f32_e32 v0, 1.0, v0
	v_rcp_f32_e32 v36, v0
	v_mul_f32_e32 v0, 0xbfb8aa3b, v52
	v_exp_f32_e32 v0, v0
	v_mul_f32_e32 v53, v53, v6
	v_mul_f32_e32 v21, v21, v6
	v_mul_f32_e32 v23, v23, v6
	v_add_f32_e32 v0, 1.0, v0
	v_rcp_f32_e32 v8, v0
	v_mul_f32_e32 v27, v27, v6
	v_mul_f32_e32 v19, v19, v6
	v_pk_mul_f32 v[64:65], v[36:37], v[64:65]
	v_pk_mul_f32 v[52:53], v[8:9], v[52:53]
	v_mul_f32_e32 v36, v64, v65
	v_mul_f32_e32 v8, v52, v53
	v_lshlrev_b32_e32 v52, 16, v57
	v_mul_f32_e32 v0, 0xbfb8aa3b, v52
	v_exp_f32_e32 v0, v0
	v_mul_f32_e32 v53, v54, v6
	v_add_f32_e32 v0, 1.0, v0
	v_rcp_f32_e32 v34, v0
	s_nop 0
	v_pk_mul_f32 v[52:53], v[34:35], v[52:53]
	s_nop 0
	v_mul_f32_e32 v34, v52, v53
	v_and_b32_e32 v52, 0xffff0000, v57
	v_mul_f32_e32 v0, 0xbfb8aa3b, v52
	v_exp_f32_e32 v0, v0
	v_mul_f32_e32 v53, v55, v6
	v_add_f32_e32 v0, 1.0, v0
	v_rcp_f32_e32 v10, v0
	s_nop 0
	v_pk_mul_f32 v[52:53], v[10:11], v[52:53]
	s_nop 0
	v_mul_f32_e32 v10, v52, v53
	v_lshlrev_b32_e32 v52, 16, v58
	v_mul_f32_e32 v0, 0xbfb8aa3b, v52
	v_exp_f32_e32 v0, v0
	v_mul_f32_e32 v53, v24, v6
	v_add_f32_e32 v0, 1.0, v0
	v_rcp_f32_e32 v32, v0
	s_nop 0
	v_pk_mul_f32 v[52:53], v[32:33], v[52:53]
	s_nop 0
	v_mul_f32_e32 v24, v52, v53
	v_and_b32_e32 v52, 0xffff0000, v58
	v_mul_f32_e32 v0, 0xbfb8aa3b, v52
	v_exp_f32_e32 v0, v0
	v_mul_f32_e32 v53, v25, v6
	v_add_f32_e32 v0, 1.0, v0
	v_rcp_f32_e32 v12, v0
	s_nop 0
	v_pk_mul_f32 v[52:53], v[12:13], v[52:53]
	s_nop 0
	v_mul_f32_e32 v12, v52, v53
	v_lshlrev_b32_e32 v52, 16, v59
	v_mul_f32_e32 v0, 0xbfb8aa3b, v52
	v_exp_f32_e32 v0, v0
	v_mul_f32_e32 v53, v26, v6
	v_and_b32_e32 v26, 0xffff0000, v59
	v_cvt_pk_bf16_f32 v24, v24, v12
	v_add_f32_e32 v0, 1.0, v0
	v_rcp_f32_e32 v30, v0
	v_mul_f32_e32 v0, 0xbfb8aa3b, v26
	v_exp_f32_e32 v0, v0
	v_pk_mul_f32 v[52:53], v[30:31], v[52:53]
	s_nop 0
	v_mul_f32_e32 v25, v52, v53
	v_add_f32_e32 v0, 1.0, v0
	s_nop 0
	v_lshlrev_b32_e32 v52, 16, v60
	v_rcp_f32_e32 v14, v0
	v_mul_f32_e32 v0, 0xbfb8aa3b, v52
	v_exp_f32_e32 v0, v0
	v_mul_f32_e32 v53, v20, v6
	v_and_b32_e32 v20, 0xffff0000, v60
	v_pk_mul_f32 v[26:27], v[14:15], v[26:27]
	v_add_f32_e32 v0, 1.0, v0
	v_rcp_f32_e32 v44, v0
	v_mul_f32_e32 v0, 0xbfb8aa3b, v20
	v_exp_f32_e32 v0, v0
	v_mul_f32_e32 v26, v26, v27
	v_cvt_pk_bf16_f32 v25, v25, v26
	v_pk_mul_f32 v[52:53], v[44:45], v[52:53]
	v_add_f32_e32 v0, 1.0, v0
	v_rcp_f32_e32 v0, v0
	v_mul_f32_e32 v14, v52, v53
	v_pk_mul_f32 v[20:21], v[0:1], v[20:21]
	s_nop 0
	v_mul_f32_e32 v0, v20, v21
	v_lshlrev_b32_e32 v20, 16, v61
	v_mul_f32_e32 v2, 0xbfb8aa3b, v20
	v_exp_f32_e32 v2, v2
	v_mul_f32_e32 v21, v22, v6
	v_and_b32_e32 v22, 0xffff0000, v61
	v_add_f32_e32 v2, 1.0, v2
	v_rcp_f32_e32 v42, v2
	v_mul_f32_e32 v2, 0xbfb8aa3b, v22
	v_exp_f32_e32 v2, v2
	v_pk_mul_f32 v[20:21], v[42:43], v[20:21]
	s_nop 0
	v_mul_f32_e32 v20, v20, v21
	v_add_f32_e32 v2, 1.0, v2
	v_rcp_f32_e32 v2, v2
	s_nop 0
	v_pk_mul_f32 v[22:23], v[2:3], v[22:23]
	s_nop 0
	v_mul_f32_e32 v2, v22, v23
	v_lshlrev_b32_e32 v22, 16, v62
	v_mul_f32_e32 v4, 0xbfb8aa3b, v22
	v_exp_f32_e32 v4, v4
	v_mul_f32_e32 v23, v16, v6
	v_add_f32_e32 v4, 1.0, v4
	v_rcp_f32_e32 v40, v4
	s_nop 0
	v_pk_mul_f32 v[22:23], v[40:41], v[22:23]
	s_nop 0
	v_mul_f32_e32 v16, v22, v23
	v_and_b32_e32 v22, 0xffff0000, v62
	v_mul_f32_e32 v4, 0xbfb8aa3b, v22
	v_exp_f32_e32 v4, v4
	v_mul_f32_e32 v23, v17, v6
	v_add_f32_e32 v4, 1.0, v4
	v_rcp_f32_e32 v4, v4
	s_nop 0
	v_pk_mul_f32 v[22:23], v[4:5], v[22:23]
	s_nop 0
	v_mul_f32_e32 v4, v22, v23
	v_mul_f32_e32 v23, v18, v6
	v_and_b32_e32 v18, 0xffff0000, v63
	v_mul_f32_e32 v6, 0xbfb8aa3b, v18
	v_exp_f32_e32 v6, v6
	v_lshlrev_b32_e32 v22, 16, v63
	v_mul_f32_e32 v17, 0xbfb8aa3b, v22
	v_exp_f32_e32 v17, v17
	v_add_f32_e32 v6, 1.0, v6
	v_rcp_f32_e32 v6, v6
	v_add_f32_e32 v17, 1.0, v17
	v_rcp_f32_e32 v38, v17
	v_pk_mul_f32 v[18:19], v[6:7], v[18:19]
	v_pk_mul_f32 v[22:23], v[38:39], v[22:23]
	v_mul_f32_e32 v6, v18, v19
	v_lshl_add_u64 v[18:19], v[28:29], 0, v[46:47]
	v_add_co_u32_e32 v26, vcc, s5, v18
	v_lshl_add_u64 v[46:47], v[46:47], 0, s[84:85]
	s_nop 0
	v_addc_co_u32_e32 v27, vcc, 0, v19, vcc
	v_mul_f32_e32 v17, v22, v23
	v_cvt_pk_bf16_f32 v22, v36, v8
	v_cvt_pk_bf16_f32 v23, v34, v10
	global_store_dwordx4 v[26:27], v[22:25], off offset:2048
	v_cvt_pk_bf16_f32 v18, v14, v0
	v_cvt_pk_bf16_f32 v19, v20, v2
	v_cvt_pk_bf16_f32 v20, v16, v4
	v_cvt_pk_bf16_f32 v21, v17, v6
	global_store_dwordx4 v[26:27], v[18:21], off offset:2064
	v_lshl_add_u64 v[16:17], v[28:29], 0, v[50:51]
	v_lshl_add_u64 v[18:19], v[16:17], 0, s[8:9]
	v_add_co_u32_e32 v16, vcc, 0x28e00000, v16
	s_mov_b64 s[6:7], 0x13c03800
	s_nop 0
	v_addc_co_u32_e32 v17, vcc, 0, v17, vcc
	s_waitcnt vmcnt(6)
; __device__ __forceinline__ float bflo(unsigned w) { return __uint_as_float(w << 16); }
; __device__ __forceinline__ float bfhi(unsigned w) { return __uint_as_float(w & 0xffff0000u); }
; __device__ __forceinline__ float rsq_f(float x) { return __builtin_amdgcn_rsqf(x); }
; __device__ __forceinline__ void onorm_pass(const float* obuf, const bf16_t* z, const float* ong, bf16_t* ycat, int gw, int NGW, int lane) {
;     ...
;     for (int row = gw; row < MP; row += NGW) {
;         const float* op = obuf + (size_t)row * 1024 + lane * 16; const bf16_t* zp = z + (size_t)row * NZ + 7168 + lane * 16;
;         f32x4 v[4]; float ss = 0.f;
; #pragma unroll
;         for (int i = 0; i < 4; ++i) { v[i] = *(const f32x4*)(op + 4 * i); ss += (v[i].x * v[i].x + v[i].y * v[i].y) + (v[i].z * v[i].z + v[i].w * v[i].w); }
;         const u32x4 g0 = *(const u32x4*)zp, g1 = *(const u32x4*)(zp + 8);
;         ss += __builtin_bit_cast(float, __builtin_amdgcn_update_dpp(0, __builtin_bit_cast(int, ss), 0xB1, 0xF, 0xF, true));
;         ss += __builtin_bit_cast(float, __builtin_amdgcn_update_dpp(0, __builtin_bit_cast(int, ss), 0x4E, 0xF, 0xF, true));
;         ss += __builtin_bit_cast(float, __builtin_amdgcn_update_dpp(0, __builtin_bit_cast(int, ss), 0x141, 0xF, 0xF, true));
;         const float rstd = rsq_f(ss * (1.f / HD) + EPS);
;         float y[16];
;         y[0] = v[0].x * rstd * g[0].x * silu_f(bflo(g0.x)); y[1] = v[0].y * rstd * g[0].y * silu_f(bfhi(g0.x)); y[2] = v[0].z * rstd * g[0].z * silu_f(bflo(g0.y)); y[3] = v[0].w * rstd * g[0].w * silu_f(bfhi(g0.y));
;         y[4] = v[1].x * rstd * g[1].x * silu_f(bflo(g0.z)); y[5] = v[1].y * rstd * g[1].y * silu_f(bfhi(g0.z)); y[6] = v[1].z * rstd * g[1].z * silu_f(bflo(g0.w)); y[7] = v[1].w * rstd * g[1].w * silu_f(bfhi(g0.w));
;         y[8] = v[2].x * rstd * g[2].x * silu_f(bflo(g1.x)); y[9] = v[2].y * rstd * g[2].y * silu_f(bfhi(g1.x)); y[10] = v[2].z * rstd * g[2].z * silu_f(bflo(g1.y)); y[11] = v[2].w * rstd * g[2].w * silu_f(bfhi(g1.y));
;         y[12] = v[3].x * rstd * g[3].x * silu_f(bflo(g1.z)); y[13] = v[3].y * rstd * g[3].y * silu_f(bfhi(g1.z)); y[14] = v[3].z * rstd * g[3].z * silu_f(bflo(g1.w)); y[15] = v[3].w * rstd * g[3].w * silu_f(bfhi(g1.w));
;         bf16_t* yp = ycat + (size_t)row * DM + 1024 + lane * 16;
;         *(u32x4*)yp = pack8(y); *(u32x4*)(yp + 8) = pack8(y + 8);
	v_mov_b32_e32 v52, v140
	v_mov_b32_e32 v53, v141
	v_mov_b32_e32 v54, v142
	v_mov_b32_e32 v55, v143
	v_mov_b32_e32 v20, v148
	v_mov_b32_e32 v21, v149
	v_mov_b32_e32 v22, v150
	v_mov_b32_e32 v23, v151
	v_mov_b32_e32 v24, v144
	v_mov_b32_e32 v25, v145
	v_mov_b32_e32 v26, v146
	v_mov_b32_e32 v27, v147
	s_nop 0
	v_mov_b32_e32 v16, v156
	v_mov_b32_e32 v17, v157
	v_mov_b32_e32 v18, v158
	v_mov_b32_e32 v19, v159
	s_mov_b32 s5, 0x20300000
	s_addk_i32 s4, 0x400
	v_lshl_add_u64 v[50:51], v[50:51], 0, s[84:85]
	s_cmpk_gt_i32 s4, 0x1bff
	s_nop 0
	v_pk_mul_f32 v[56:57], v[54:55], v[54:55]
	v_pk_mul_f32 v[58:59], v[52:53], v[52:53]
	s_nop 0
	v_mul_f32_e32 v0, v16, v16
	v_pk_mov_b32 v[60:61], v[58:59], v[56:57] op_sel:[1,0]
	v_mov_b32_e32 v59, v57
	v_pk_add_f32 v[56:57], v[60:61], v[58:59]
	v_pk_mul_f32 v[58:59], v[26:27], v[26:27]
	v_pk_mul_f32 v[60:61], v[24:25], v[24:25]
	v_mul_f32_e32 v2, v17, v17
	v_pk_mov_b32 v[62:63], v[60:61], v[58:59] op_sel:[1,0]
	v_mov_b32_e32 v61, v59
	v_pk_add_f32 v[58:59], v[62:63], v[60:61]
	v_pk_add_f32 v[56:57], v[56:57], v[56:57] op_sel:[0,1] op_sel_hi:[1,0]
	v_pk_add_f32 v[58:59], v[58:59], v[58:59] op_sel:[0,1] op_sel_hi:[1,0]
	v_mov_b32_e32 v57, v0
	v_mov_b32_e32 v59, v2
	v_mul_f32_e32 v0, v21, v21
	v_pk_add_f32 v[56:57], v[56:57], v[58:59]
	v_pk_fma_f32 v[58:59], v[20:21], v[20:21], v[0:1] op_sel_hi:[1,1,0]
	v_mul_f32_e32 v0, v23, v23
	v_mul_f32_e32 v4, v18, v18
	v_mul_f32_e32 v6, v19, v19
	v_pk_fma_f32 v[60:61], v[22:23], v[22:23], v[0:1] op_sel_hi:[1,1,0]
	v_mov_b32_e32 v59, v4
	v_mov_b32_e32 v61, v6
	v_pk_add_f32 v[58:59], v[58:59], v[60:61]
	s_nop 0
	v_pk_add_f32 v[56:57], v[56:57], v[58:59]
	s_nop 0
	v_add_f32_e32 v0, v56, v57
	v_lshl_add_u64 v[56:57], v[28:29], 0, v[48:49]
	v_lshl_add_u64 v[60:61], v[56:57], 0, s[6:7]
	v_add_co_u32_e32 v56, vcc, s76, v56
	v_add_f32_dpp v0, v0, v0 quad_perm:[1,0,3,2] row_mask:0xf bank_mask:0xf bound_ctrl:1
	s_nop 0
	v_addc_co_u32_e32 v57, vcc, 0, v57, vcc
	v_mov_b32_e32 v56, v160
	v_mov_b32_e32 v57, v161
	v_mov_b32_e32 v58, v162
	v_mov_b32_e32 v59, v163
	s_nop 0
	v_mov_b32_e32 v60, v164
	v_mov_b32_e32 v61, v165
	v_mov_b32_e32 v62, v166
	v_mov_b32_e32 v63, v167
	v_add_f32_dpp v0, v0, v0 quad_perm:[2,3,0,1] row_mask:0xf bank_mask:0xf bound_ctrl:1
	v_lshl_add_u64 v[48:49], v[48:49], 0, s[60:61]
	s_nop 0
	v_lshlrev_b32_e32 v64, 16, v56
	v_add_f32_dpp v0, v0, v0 row_half_mirror row_mask:0xf bank_mask:0xf bound_ctrl:1
	v_fmamk_f32 v0, v0, 0x3c000000, v194
	v_rsq_f32_e32 v6, v0
	v_mul_f32_e32 v0, 0xbfb8aa3b, v64
	v_exp_f32_e32 v0, v0
	v_mul_f32_e32 v65, v52, v6
	v_and_b32_e32 v52, 0xffff0000, v56
	v_add_f32_e32 v0, 1.0, v0
	v_rcp_f32_e32 v36, v0
	v_mul_f32_e32 v0, 0xbfb8aa3b, v52
	v_exp_f32_e32 v0, v0
	v_mul_f32_e32 v53, v53, v6
	v_mul_f32_e32 v21, v21, v6
	v_mul_f32_e32 v23, v23, v6
	v_add_f32_e32 v0, 1.0, v0
	v_rcp_f32_e32 v8, v0
	v_mul_f32_e32 v27, v27, v6
	v_mul_f32_e32 v19, v19, v6
	v_pk_mul_f32 v[64:65], v[36:37], v[64:65]
	v_pk_mul_f32 v[52:53], v[8:9], v[52:53]
	v_mul_f32_e32 v36, v64, v65
	v_mul_f32_e32 v8, v52, v53
	v_lshlrev_b32_e32 v52, 16, v57
	v_mul_f32_e32 v0, 0xbfb8aa3b, v52
	v_exp_f32_e32 v0, v0
	v_mul_f32_e32 v53, v54, v6
	v_add_f32_e32 v0, 1.0, v0
	v_rcp_f32_e32 v34, v0
	s_nop 0
	v_pk_mul_f32 v[52:53], v[34:35], v[52:53]
	s_nop 0
	v_mul_f32_e32 v34, v52, v53
	v_and_b32_e32 v52, 0xffff0000, v57
	v_mul_f32_e32 v0, 0xbfb8aa3b, v52
	v_exp_f32_e32 v0, v0
	v_mul_f32_e32 v53, v55, v6
	v_add_f32_e32 v0, 1.0, v0
	v_rcp_f32_e32 v10, v0
	s_nop 0
	v_pk_mul_f32 v[52:53], v[10:11], v[52:53]
	s_nop 0
	v_mul_f32_e32 v10, v52, v53
	v_lshlrev_b32_e32 v52, 16, v58
	v_mul_f32_e32 v0, 0xbfb8aa3b, v52
	v_exp_f32_e32 v0, v0
	v_mul_f32_e32 v53, v24, v6
	v_add_f32_e32 v0, 1.0, v0
	v_rcp_f32_e32 v32, v0
	s_nop 0
	v_pk_mul_f32 v[52:53], v[32:33], v[52:53]
	s_nop 0
	v_mul_f32_e32 v24, v52, v53
	v_and_b32_e32 v52, 0xffff0000, v58
	v_mul_f32_e32 v0, 0xbfb8aa3b, v52
	v_exp_f32_e32 v0, v0
	v_mul_f32_e32 v53, v25, v6
	v_add_f32_e32 v0, 1.0, v0
	v_rcp_f32_e32 v12, v0
	s_nop 0
	v_pk_mul_f32 v[52:53], v[12:13], v[52:53]
	s_nop 0
	v_mul_f32_e32 v12, v52, v53
	v_lshlrev_b32_e32 v52, 16, v59
	v_mul_f32_e32 v0, 0xbfb8aa3b, v52
	v_exp_f32_e32 v0, v0
	v_mul_f32_e32 v53, v26, v6
	v_and_b32_e32 v26, 0xffff0000, v59
	v_cvt_pk_bf16_f32 v24, v24, v12
	v_add_f32_e32 v0, 1.0, v0
	v_rcp_f32_e32 v30, v0
	v_mul_f32_e32 v0, 0xbfb8aa3b, v26
	v_exp_f32_e32 v0, v0
	v_pk_mul_f32 v[52:53], v[30:31], v[52:53]
	s_nop 0
	v_mul_f32_e32 v25, v52, v53
	v_add_f32_e32 v0, 1.0, v0
	s_nop 0
	v_lshlrev_b32_e32 v52, 16, v60
	v_rcp_f32_e32 v14, v0
	v_mul_f32_e32 v0, 0xbfb8aa3b, v52
	v_exp_f32_e32 v0, v0
	v_mul_f32_e32 v53, v20, v6
	v_and_b32_e32 v20, 0xffff0000, v60
	v_pk_mul_f32 v[26:27], v[14:15], v[26:27]
	v_add_f32_e32 v0, 1.0, v0
	v_rcp_f32_e32 v44, v0
	v_mul_f32_e32 v0, 0xbfb8aa3b, v20
	v_exp_f32_e32 v0, v0
	v_mul_f32_e32 v26, v26, v27
	v_cvt_pk_bf16_f32 v25, v25, v26
	v_pk_mul_f32 v[52:53], v[44:45], v[52:53]
	v_add_f32_e32 v0, 1.0, v0
	v_rcp_f32_e32 v0, v0
	v_mul_f32_e32 v14, v52, v53
	v_pk_mul_f32 v[20:21], v[0:1], v[20:21]
	s_nop 0
	v_mul_f32_e32 v0, v20, v21
	v_lshlrev_b32_e32 v20, 16, v61
	v_mul_f32_e32 v2, 0xbfb8aa3b, v20
	v_exp_f32_e32 v2, v2
	v_mul_f32_e32 v21, v22, v6
	v_and_b32_e32 v22, 0xffff0000, v61
	v_add_f32_e32 v2, 1.0, v2
	v_rcp_f32_e32 v42, v2
	v_mul_f32_e32 v2, 0xbfb8aa3b, v22
	v_exp_f32_e32 v2, v2
	v_pk_mul_f32 v[20:21], v[42:43], v[20:21]
	s_nop 0
	v_mul_f32_e32 v20, v20, v21
	v_add_f32_e32 v2, 1.0, v2
	v_rcp_f32_e32 v2, v2
	s_nop 0
	v_pk_mul_f32 v[22:23], v[2:3], v[22:23]
	s_nop 0
	v_mul_f32_e32 v2, v22, v23
	v_lshlrev_b32_e32 v22, 16, v62
	v_mul_f32_e32 v4, 0xbfb8aa3b, v22
	v_exp_f32_e32 v4, v4
	v_mul_f32_e32 v23, v16, v6
	v_add_f32_e32 v4, 1.0, v4
	v_rcp_f32_e32 v40, v4
	s_nop 0
	v_pk_mul_f32 v[22:23], v[40:41], v[22:23]
	s_nop 0
	v_mul_f32_e32 v16, v22, v23
	v_and_b32_e32 v22, 0xffff0000, v62
	v_mul_f32_e32 v4, 0xbfb8aa3b, v22
	v_exp_f32_e32 v4, v4
	v_mul_f32_e32 v23, v17, v6
	v_add_f32_e32 v4, 1.0, v4
	v_rcp_f32_e32 v4, v4
	s_nop 0
	v_pk_mul_f32 v[22:23], v[4:5], v[22:23]
	s_nop 0
	v_mul_f32_e32 v4, v22, v23
	v_mul_f32_e32 v23, v18, v6
	v_and_b32_e32 v18, 0xffff0000, v63
	v_mul_f32_e32 v6, 0xbfb8aa3b, v18
	v_exp_f32_e32 v6, v6
	v_lshlrev_b32_e32 v22, 16, v63
	v_mul_f32_e32 v17, 0xbfb8aa3b, v22
	v_exp_f32_e32 v17, v17
	v_add_f32_e32 v6, 1.0, v6
	v_rcp_f32_e32 v6, v6
	v_add_f32_e32 v17, 1.0, v17
	v_rcp_f32_e32 v38, v17
	v_pk_mul_f32 v[18:19], v[6:7], v[18:19]
	v_pk_mul_f32 v[22:23], v[38:39], v[22:23]
	v_mul_f32_e32 v6, v18, v19
	v_lshl_add_u64 v[18:19], v[28:29], 0, v[46:47]
	v_add_co_u32_e32 v26, vcc, s5, v18
	v_lshl_add_u64 v[46:47], v[46:47], 0, s[84:85]
	s_nop 0
	v_addc_co_u32_e32 v27, vcc, 0, v19, vcc
	v_mul_f32_e32 v17, v22, v23
	v_cvt_pk_bf16_f32 v22, v36, v8
	v_cvt_pk_bf16_f32 v23, v34, v10
	global_store_dwordx4 v[26:27], v[22:25], off offset:2048
	v_cvt_pk_bf16_f32 v18, v14, v0
	v_cvt_pk_bf16_f32 v19, v20, v2
	v_cvt_pk_bf16_f32 v20, v16, v4
	v_cvt_pk_bf16_f32 v21, v17, v6
	global_store_dwordx4 v[26:27], v[18:21], off offset:2064
